# mid8 stack plus cross-row prefetch in the four rowwise phases (P3/P11/P14/P16): next prompt row's residual+T words loaded into a spare register buffer while the current row is normalised
# baseline (speedup 1.0000x reference)
;     ...
;     for (int r = gw; r < M; r += NGW) {
;         f32x4 v[8];
;         if (RES) { const GAS v2u* rp = (const GAS v2u*)(RES + (size_t)r * D) + lane;
; #pragma unroll
;             for (int j = 0; j < 8; ++j) { const v2u w = rp[64 * j]; v[j] = (f32x4){bflo(w.x), bfhi(w.x), bflo(w.y), bfhi(w.y)}; } }
;         else { const GAS f32x4* rp = (const GAS f32x4*)xrow(a, r) + lane;
; #pragma unroll
;             for (int j = 0; j < 8; ++j) v[j] = rp[64 * j]; }
;         if (MODE != 0) {
;             const GAS v2u* tp = (const GAS v2u*)(T + (size_t)r * D) + lane;
;             f32x4 t[8]; float ss = 0.f;
;             if (TSRC != 0 && r >= NP) {
;                 const GAS f32x4* sp = (const GAS f32x4*)(WSP(float, WS_SLAB) + (size_t)(r - NP) * D) + lane;
; #pragma unroll
;                 for (int j = 0; j < 8; ++j) t[j] = sp[64 * j];
;                 _Pragma("unroll 1") for (int s = 1; s < nslab; ++s) { sp += (size_t)NS * D / 4;
; #pragma unroll
;                     for (int j = 0; j < 8; ++j) t[j] += sp[64 * j]; }
;                 if (TSRC == 2) { const GAS v2u* pp = (const GAS v2u*)(PUP + (size_t)r * D) + lane;
; #pragma unroll
;                     for (int j = 0; j < 8; ++j) { const v2u pw = pp[64 * j]; const f32x4 p = (f32x4){bflo(pw.x), bfhi(pw.x), bflo(pw.y), bfhi(pw.y)}; t[j] = (f32x4){sigmf(t[j][0]), sigmf(t[j][1]), sigmf(t[j][2]), sigmf(t[j][3])} * p; } }
; #pragma unroll
;                 for (int j = 0; j < 8; ++j) ss += dot4(t[j], t[j]);
;             } else {
; #pragma unroll
;                 for (int j = 0; j < 8; ++j) { const v2u tw = tp[64 * j]; t[j] = (f32x4){bflo(tw.x), bfhi(tw.x), bflo(tw.y), bfhi(tw.y)}; ss += dot4(t[j], t[j]); }
;             }
;             ss = wave_sum(ss);
;             const float rs = sc * (1.0f / sqrtf(ss * (1.0f / D) + EPS));
; #pragma unroll
;             for (int j = 0; j < 8; ++j) { const f32x4 g = gpo[j]; v[j] = v[j] + (t[j] * rs) * g;
;                 if (MODE == 2) ((GAS f32x4*)(Yout + (size_t)r * D))[lane + 64 * j] = v[j];
;                 else { v2u w; w.x = pk2(v[j][0], v[j][1]); w.y = pk2(v[j][2], v[j][3]); ((GAS v2u*)(Hout + (size_t)r * D))[lane + 64 * j] = w;
;                        v[j] = (f32x4){bflo(w.x), bfhi(w.x), bflo(w.y), bfhi(w.y)}; } }
;         }
;         if (MODE != 2) {
;             float ss = 0.f;
; #pragma unroll
;             for (int j = 0; j < 8; ++j) ss += dot4(v[j], v[j]);
.LBB0_271:
	ds_bpermute_b32 v143, v144, v142
	s_add_i32 s78, s8, s3
	s_cmpk_gt_i32 s78, 0x1fff
	s_cbranch_scc1 .Lrowpf272_skip
	s_lshl_b32 s84, s78, 12
	s_mov_b32 s85, 0
	s_lshl_b32 s78, s78, 13
	s_add_u32 s78, s36, s78
	s_addc_u32 s79, s37, 0
	global_load_dwordx4 v[186:189], v130, s[78:79]
	global_load_dwordx4 v[190:193], v130, s[78:79] offset:1024
	global_load_dwordx4 v[194:197], v130, s[78:79] offset:2048
	global_load_dwordx4 v[198:201], v130, s[78:79] offset:3072
	s_nop 0
	s_add_u32 s78, s78, 0x1000
	s_addc_u32 s79, s79, 0
	global_load_dwordx4 v[202:205], v130, s[78:79]
	global_load_dwordx4 v[206:209], v130, s[78:79] offset:1024
	global_load_dwordx4 v[210:213], v130, s[78:79] offset:2048
	global_load_dwordx4 v[214:217], v130, s[78:79] offset:3072
	v_lshl_add_u64 v[234:235], v[132:133], 0, s[84:85]
	global_load_dwordx2 v[218:219], v[234:235], off
	global_load_dwordx2 v[220:221], v[234:235], off offset:512
	global_load_dwordx2 v[222:223], v[234:235], off offset:1024
	global_load_dwordx2 v[224:225], v[234:235], off offset:1536
	global_load_dwordx2 v[226:227], v[234:235], off offset:2048
	global_load_dwordx2 v[228:229], v[234:235], off offset:2560
	global_load_dwordx2 v[230:231], v[234:235], off offset:3072
	global_load_dwordx2 v[232:233], v[234:235], off offset:3584
.Lrowpf272_skip:
	s_lshl_b64 s[14:15], s[14:15], 1
	s_add_i32 s8, s8, s3
	s_add_i32 s12, s12, s3
	s_cmpk_lt_i32 s8, 0x2200
	s_waitcnt lgkmcnt(0)
	v_add_f32_e32 v142, v142, v143
	ds_bpermute_b32 v143, v145, v142
	s_waitcnt lgkmcnt(0)
	v_add_f32_e32 v142, v142, v143
	ds_bpermute_b32 v143, v146, v142
	s_waitcnt lgkmcnt(0)
	v_add_f32_e32 v142, v142, v143
	ds_bpermute_b32 v143, v147, v142
	s_waitcnt lgkmcnt(0)
	v_add_f32_e32 v142, v142, v143
	ds_bpermute_b32 v143, v148, v142
	s_waitcnt lgkmcnt(0)
	v_add_f32_e32 v142, v142, v143
	ds_bpermute_b32 v143, v149, v142
	s_waitcnt lgkmcnt(0)
	v_add_f32_e32 v142, v142, v143
	v_fmamk_f32 v142, v142, 0x3a000000, v150
	v_mul_f32_e32 v143, 0x4f800000, v142
	v_cmp_gt_f32_e32 vcc, s18, v142
	s_nop 1
	v_cndmask_b32_e32 v142, v142, v143, vcc
	v_sqrt_f32_e32 v143, v142
	s_nop 0
	v_add_u32_e32 v153, -1, v143
	v_add_u32_e32 v154, 1, v143
	v_fma_f32 v155, -v153, v143, v142
	v_fma_f32 v156, -v154, v143, v142
	v_cmp_ge_f32_e64 s[6:7], 0, v155
	s_nop 1
	v_cndmask_b32_e64 v143, v143, v153, s[6:7]
	v_cmp_lt_f32_e64 s[6:7], 0, v156
	s_nop 1
	v_cndmask_b32_e64 v143, v143, v154, s[6:7]
	v_mul_f32_e32 v153, 0x37800000, v143
	v_cndmask_b32_e32 v143, v143, v153, vcc
	v_cmp_class_f32_e32 vcc, v142, v151
	s_nop 1
	v_cndmask_b32_e32 v142, v143, v142, vcc
	v_div_scale_f32 v143, s[6:7], v142, v142, 1.0
	v_rcp_f32_e32 v153, v143
	v_div_scale_f32 v154, vcc, 1.0, v142, 1.0
	v_fma_f32 v155, -v143, v153, 1.0
	v_fmac_f32_e32 v153, v155, v153
	v_mul_f32_e32 v155, v154, v153
	v_fma_f32 v156, -v143, v155, v154
	v_fmac_f32_e32 v155, v156, v153
	v_fma_f32 v143, -v143, v155, v154
	v_div_fmas_f32 v143, v143, v153, v155
	v_div_fixup_f32 v142, v143, v142, 1.0
	v_mul_f32_e32 v142, 0.5, v142
	v_pk_mul_f32 v[110:111], v[110:111], v[142:143] op_sel_hi:[1,0]
	v_pk_mul_f32 v[122:123], v[122:123], v[142:143] op_sel_hi:[1,0]
	v_pk_mul_f32 v[124:125], v[124:125], v[142:143] op_sel_hi:[1,0]
	v_pk_mul_f32 v[126:127], v[126:127], v[142:143] op_sel_hi:[1,0]
	v_pk_fma_f32 v[82:83], v[26:27], v[110:111], v[82:83]
	v_pk_mul_f32 v[128:129], v[128:129], v[142:143] op_sel_hi:[1,0]
	v_pk_fma_f32 v[96:97], v[4:5], v[124:125], v[96:97]
	v_pk_fma_f32 v[94:95], v[2:3], v[122:123], v[94:95]
	v_pk_fma_f32 v[90:91], v[10:11], v[126:127], v[90:91]
	v_pk_mul_f32 v[114:115], v[114:115], v[142:143] op_sel_hi:[1,0]
	v_and_b32_sdwa v110, v83, v152 dst_sel:DWORD dst_unused:UNUSED_PAD src0_sel:WORD_1 src1_sel:DWORD
	v_and_b32_sdwa v111, v82, v152 dst_sel:DWORD dst_unused:UNUSED_PAD src0_sel:WORD_1 src1_sel:DWORD
	v_pk_fma_f32 v[92:93], v[12:13], v[128:129], v[92:93]
	v_and_b32_sdwa v122, v95, v152 dst_sel:DWORD dst_unused:UNUSED_PAD src0_sel:WORD_1 src1_sel:DWORD
	v_and_b32_sdwa v123, v94, v152 dst_sel:DWORD dst_unused:UNUSED_PAD src0_sel:WORD_1 src1_sel:DWORD
	v_and_b32_sdwa v125, v96, v152 dst_sel:DWORD dst_unused:UNUSED_PAD src0_sel:WORD_1 src1_sel:DWORD
	v_and_b32_sdwa v126, v91, v152 dst_sel:DWORD dst_unused:UNUSED_PAD src0_sel:WORD_1 src1_sel:DWORD
	v_pk_fma_f32 v[86:87], v[18:19], v[114:115], v[86:87]
	v_pk_mul_f32 v[112:113], v[112:113], v[142:143] op_sel_hi:[1,0]
	v_add3_u32 v83, v83, v110, s19
	v_add3_u32 v114, v82, v111, s19
	v_pk_mul_f32 v[110:111], v[118:119], v[142:143] op_sel_hi:[1,0]
	v_pk_mul_f32 v[98:99], v[98:99], v[142:143] op_sel_hi:[1,0]
	v_and_b32_sdwa v124, v97, v152 dst_sel:DWORD dst_unused:UNUSED_PAD src0_sel:WORD_1 src1_sel:DWORD
	v_and_b32_sdwa v127, v90, v152 dst_sel:DWORD dst_unused:UNUSED_PAD src0_sel:WORD_1 src1_sel:DWORD
	v_add3_u32 v95, v95, v122, s19
	v_add3_u32 v122, v94, v123, s19
	v_add3_u32 v123, v96, v125, s19
	v_add3_u32 v91, v91, v126, s19
	v_and_b32_sdwa v125, v93, v152 dst_sel:DWORD dst_unused:UNUSED_PAD src0_sel:WORD_1 src1_sel:DWORD
	v_pk_fma_f32 v[84:85], v[28:29], v[112:113], v[84:85]
	v_pk_mul_f32 v[112:113], v[120:121], v[142:143] op_sel_hi:[1,0]
	v_pk_fma_f32 v[78:79], v[34:35], v[110:111], v[78:79]
	v_pk_mul_f32 v[102:103], v[102:103], v[142:143] op_sel_hi:[1,0]
	v_pk_mul_f32 v[100:101], v[100:101], v[142:143] op_sel_hi:[1,0]
	v_pk_fma_f32 v[66:67], v[58:59], v[98:99], v[66:67]
	v_add3_u32 v97, v97, v124, s19
	v_add3_u32 v124, v90, v127, s19
	v_and_b32_e32 v95, 0xffff0000, v95
	v_and_b32_e32 v91, 0xffff0000, v91
	v_and_b32_sdwa v126, v92, v152 dst_sel:DWORD dst_unused:UNUSED_PAD src0_sel:WORD_1 src1_sel:DWORD
	v_add3_u32 v93, v93, v125, s19
; #define GAS __attribute__((address_space(1)))
; __device__ __forceinline__ unsigned pk2(float lo, float hi) { return f2bf(lo) | (f2bf(hi) << 16); }
; __device__ __forceinline__ float bflo(unsigned w) { return __uint_as_float(w << 16); }
; __device__ __forceinline__ float bfhi(unsigned w) { return __uint_as_float(w & 0xffff0000u); }
; __device__ __forceinline__ float dot4(f32x4 a, f32x4 b) { return (a[0] * b[0] + a[1] * b[1]) + (a[2] * b[2] + a[3] * b[3]); }
;     ...
;             for (int j = 0; j < 8; ++j) { const f32x4 g = gpo[j]; v[j] = v[j] + (t[j] * rs) * g;
;                 if (MODE == 2) ((GAS f32x4*)(Yout + (size_t)r * D))[lane + 64 * j] = v[j];
;                 else { v2u w; w.x = pk2(v[j][0], v[j][1]); w.y = pk2(v[j][2], v[j][3]); ((GAS v2u*)(Hout + (size_t)r * D))[lane + 64 * j] = w;
;                        v[j] = (f32x4){bflo(w.x), bfhi(w.x), bflo(w.y), bfhi(w.y)}; } }
;         }
;         if (MODE != 2) {
;             float ss = 0.f;
; #pragma unroll
;             for (int j = 0; j < 8; ++j) ss += dot4(v[j], v[j]);
;             ss = wave_sum(ss);
	v_pk_fma_f32 v[80:81], v[36:37], v[112:113], v[80:81]
	v_and_b32_sdwa v110, v79, v152 dst_sel:DWORD dst_unused:UNUSED_PAD src0_sel:WORD_1 src1_sel:DWORD
	v_and_b32_sdwa v111, v78, v152 dst_sel:DWORD dst_unused:UNUSED_PAD src0_sel:WORD_1 src1_sel:DWORD
	v_pk_fma_f32 v[70:71], v[50:51], v[102:103], v[70:71]
	v_pk_fma_f32 v[68:69], v[60:61], v[100:101], v[68:69]
	v_and_b32_sdwa v98, v67, v152 dst_sel:DWORD dst_unused:UNUSED_PAD src0_sel:WORD_1 src1_sel:DWORD
	v_and_b32_sdwa v99, v66, v152 dst_sel:DWORD dst_unused:UNUSED_PAD src0_sel:WORD_1 src1_sel:DWORD
	v_and_b32_e32 v94, 0xffff0000, v122
	v_and_b32_e32 v97, 0xffff0000, v97
	v_and_b32_e32 v90, 0xffff0000, v124
	v_add3_u32 v125, v92, v126, s19
	v_and_b32_e32 v93, 0xffff0000, v93
	v_add3_u32 v79, v79, v110, s19
	v_add3_u32 v110, v78, v111, s19
	v_and_b32_sdwa v111, v81, v152 dst_sel:DWORD dst_unused:UNUSED_PAD src0_sel:WORD_1 src1_sel:DWORD
	v_and_b32_sdwa v112, v80, v152 dst_sel:DWORD dst_unused:UNUSED_PAD src0_sel:WORD_1 src1_sel:DWORD
	v_and_b32_sdwa v102, v71, v152 dst_sel:DWORD dst_unused:UNUSED_PAD src0_sel:WORD_1 src1_sel:DWORD
	v_and_b32_sdwa v103, v70, v152 dst_sel:DWORD dst_unused:UNUSED_PAD src0_sel:WORD_1 src1_sel:DWORD
	v_add3_u32 v67, v67, v98, s19
	v_add3_u32 v113, v66, v99, s19
	v_and_b32_sdwa v98, v69, v152 dst_sel:DWORD dst_unused:UNUSED_PAD src0_sel:WORD_1 src1_sel:DWORD
	v_and_b32_sdwa v99, v68, v152 dst_sel:DWORD dst_unused:UNUSED_PAD src0_sel:WORD_1 src1_sel:DWORD
	v_mov_b32_e32 v100, v95
	v_mov_b32_e32 v101, v91
	v_and_b32_e32 v96, 0xffff0000, v123
	v_and_b32_e32 v92, 0xffff0000, v125
	v_add3_u32 v81, v81, v111, s19
	v_add3_u32 v111, v80, v112, s19
	v_add3_u32 v71, v71, v102, s19
	v_add3_u32 v112, v70, v103, s19
	v_add3_u32 v69, v69, v98, s19
	v_add3_u32 v115, v68, v99, s19
	v_mov_b32_e32 v98, v94
	v_mov_b32_e32 v99, v90
	v_pk_mul_f32 v[100:101], v[100:101], v[100:101]
	v_mov_b32_e32 v102, v97
	v_mov_b32_e32 v103, v93
	v_pk_fma_f32 v[98:99], v[98:99], v[98:99], v[100:101]
	v_mov_b32_e32 v100, v96
	v_mov_b32_e32 v101, v92
	v_pk_mul_f32 v[102:103], v[102:103], v[102:103]
	v_pk_mul_f32 v[116:117], v[116:117], v[142:143] op_sel_hi:[1,0]
	v_pk_fma_f32 v[100:101], v[100:101], v[100:101], v[102:103]
	v_pk_fma_f32 v[88:89], v[20:21], v[116:117], v[88:89]
	v_pk_add_f32 v[98:99], v[98:99], v[100:101]
	v_and_b32_sdwa v100, v86, v152 dst_sel:DWORD dst_unused:UNUSED_PAD src0_sel:WORD_1 src1_sel:DWORD
	v_pk_add_f32 v[98:99], v[98:99], v[98:99] op_sel_hi:[0,1]
	v_and_b32_sdwa v98, v88, v152 dst_sel:DWORD dst_unused:UNUSED_PAD src0_sel:WORD_1 src1_sel:DWORD
	v_add3_u32 v116, v88, v98, s19
	v_add3_u32 v117, v86, v100, s19
	v_and_b32_sdwa v86, v89, v152 dst_sel:DWORD dst_unused:UNUSED_PAD src0_sel:WORD_1 src1_sel:DWORD
	v_and_b32_sdwa v88, v87, v152 dst_sel:DWORD dst_unused:UNUSED_PAD src0_sel:WORD_1 src1_sel:DWORD
	v_add3_u32 v86, v89, v86, s19
	v_add3_u32 v88, v87, v88, s19
	v_and_b32_e32 v87, 0xffff0000, v86
	v_and_b32_e32 v86, 0xffff0000, v88
	v_and_b32_e32 v89, 0xffff0000, v116
	v_and_b32_e32 v88, 0xffff0000, v117
	v_pk_mul_f32 v[100:101], v[86:87], v[86:87]
	v_and_b32_sdwa v98, v85, v152 dst_sel:DWORD dst_unused:UNUSED_PAD src0_sel:WORD_1 src1_sel:DWORD
	v_pk_fma_f32 v[100:101], v[88:89], v[88:89], v[100:101]
	v_add3_u32 v85, v85, v98, s19
	v_pk_add_f32 v[100:101], v[100:101], v[100:101] op_sel_hi:[0,1]
	v_and_b32_sdwa v100, v84, v152 dst_sel:DWORD dst_unused:UNUSED_PAD src0_sel:WORD_1 src1_sel:DWORD
	v_add3_u32 v118, v84, v100, s19
	v_and_b32_e32 v84, 0xffff0000, v118
	v_and_b32_e32 v82, 0xffff0000, v114
	v_and_b32_e32 v85, 0xffff0000, v85
	v_mul_f32_e32 v98, v84, v84
	v_and_b32_e32 v83, 0xffff0000, v83
	v_and_b32_e32 v79, 0xffff0000, v79
	v_and_b32_e32 v78, 0xffff0000, v110
	v_and_b32_e32 v81, 0xffff0000, v81
	v_and_b32_e32 v80, 0xffff0000, v111
	v_pk_mul_f32 v[108:109], v[108:109], v[142:143] op_sel_hi:[1,0]
	v_pk_mul_f32 v[106:107], v[106:107], v[142:143] op_sel_hi:[1,0]
	v_pk_mul_f32 v[104:105], v[104:105], v[142:143] op_sel_hi:[1,0]
	v_pk_fma_f32 v[102:103], v[84:85], v[84:85], v[98:99] op_sel_hi:[1,1,0]
	v_mul_f32_e32 v98, v82, v82
	v_pk_fma_f32 v[74:75], v[42:43], v[106:107], v[74:75]
	v_pk_fma_f32 v[76:77], v[44:45], v[108:109], v[76:77]
	v_pk_fma_f32 v[72:73], v[52:53], v[104:105], v[72:73]
	v_pk_mul_f32 v[104:105], v[78:79], v[78:79]
	v_pk_mul_f32 v[106:107], v[80:81], v[80:81]
	v_pk_fma_f32 v[108:109], v[82:83], v[82:83], v[98:99] op_sel_hi:[1,1,0]
	v_mov_b32_e32 v102, v105
	v_mov_b32_e32 v108, v104
	v_mov_b32_e32 v100, v106
	v_mov_b32_e32 v98, v107
	v_pk_add_f32 v[102:103], v[108:109], v[102:103]
	v_pk_add_f32 v[98:99], v[100:101], v[98:99]
	v_and_b32_sdwa v100, v74, v152 dst_sel:DWORD dst_unused:UNUSED_PAD src0_sel:WORD_1 src1_sel:DWORD
	v_pk_add_f32 v[98:99], v[102:103], v[98:99]
	v_add3_u32 v120, v74, v100, s19
	v_pk_add_f32 v[98:99], v[98:99], v[98:99] op_sel_hi:[0,1]
	v_and_b32_sdwa v98, v76, v152 dst_sel:DWORD dst_unused:UNUSED_PAD src0_sel:WORD_1 src1_sel:DWORD
	v_add3_u32 v119, v76, v98, s19
	v_and_b32_sdwa v74, v77, v152 dst_sel:DWORD dst_unused:UNUSED_PAD src0_sel:WORD_1 src1_sel:DWORD
	v_and_b32_sdwa v76, v75, v152 dst_sel:DWORD dst_unused:UNUSED_PAD src0_sel:WORD_1 src1_sel:DWORD
	v_add3_u32 v74, v77, v74, s19
	v_add3_u32 v76, v75, v76, s19
	v_and_b32_e32 v75, 0xffff0000, v74
	v_and_b32_e32 v74, 0xffff0000, v76
	v_and_b32_e32 v77, 0xffff0000, v119
	v_and_b32_e32 v76, 0xffff0000, v120
	v_pk_mul_f32 v[100:101], v[74:75], v[74:75]
	v_and_b32_sdwa v98, v73, v152 dst_sel:DWORD dst_unused:UNUSED_PAD src0_sel:WORD_1 src1_sel:DWORD
	v_pk_fma_f32 v[100:101], v[76:77], v[76:77], v[100:101]
	v_add3_u32 v73, v73, v98, s19
	v_pk_add_f32 v[100:101], v[100:101], v[100:101] op_sel_hi:[0,1]
	v_and_b32_sdwa v100, v72, v152 dst_sel:DWORD dst_unused:UNUSED_PAD src0_sel:WORD_1 src1_sel:DWORD
	v_add3_u32 v121, v72, v100, s19
	v_and_b32_e32 v72, 0xffff0000, v121
	v_and_b32_e32 v70, 0xffff0000, v112
	v_and_b32_e32 v73, 0xffff0000, v73
	v_mul_f32_e32 v98, v72, v72
	v_and_b32_e32 v71, 0xffff0000, v71
	v_and_b32_e32 v67, 0xffff0000, v67
	v_and_b32_e32 v66, 0xffff0000, v113
	v_and_b32_e32 v69, 0xffff0000, v69
	v_and_b32_e32 v68, 0xffff0000, v115
	v_pk_fma_f32 v[102:103], v[72:73], v[72:73], v[98:99] op_sel_hi:[1,1,0]
	v_mul_f32_e32 v98, v70, v70
	v_pk_mul_f32 v[104:105], v[66:67], v[66:67]
	v_pk_mul_f32 v[106:107], v[68:69], v[68:69]
	v_pk_fma_f32 v[108:109], v[70:71], v[70:71], v[98:99] op_sel_hi:[1,1,0]
	v_mov_b32_e32 v102, v105
	v_mov_b32_e32 v108, v104
	v_mov_b32_e32 v100, v106
	v_mov_b32_e32 v98, v107
	v_pk_add_f32 v[102:103], v[108:109], v[102:103]
	v_pk_add_f32 v[98:99], v[100:101], v[98:99]
	v_or_b32_sdwa v100, v95, v122 dst_sel:DWORD dst_unused:UNUSED_PAD src0_sel:DWORD src1_sel:WORD_1
	v_pk_add_f32 v[98:99], v[102:103], v[98:99]
	v_or_b32_sdwa v101, v97, v123 dst_sel:DWORD dst_unused:UNUSED_PAD src0_sel:DWORD src1_sel:WORD_1
	v_add_f32_e32 v98, v98, v99
	ds_bpermute_b32 v99, v144, v98
	v_or_b32_sdwa v105, v69, v115 dst_sel:DWORD dst_unused:UNUSED_PAD src0_sel:DWORD src1_sel:WORD_1
	s_waitcnt lgkmcnt(0)
; #define GAS __attribute__((address_space(1)))
; __device__ __forceinline__ unsigned pk2(float lo, float hi) { return f2bf(lo) | (f2bf(hi) << 16); }
; __device__ __forceinline__ float bflo(unsigned w) { return __uint_as_float(w << 16); }
; __device__ __forceinline__ float bfhi(unsigned w) { return __uint_as_float(w & 0xffff0000u); }
; __device__ __forceinline__ float dot4(f32x4 a, f32x4 b) { return (a[0] * b[0] + a[1] * b[1]) + (a[2] * b[2] + a[3] * b[3]); }
;     ...
;                 else { v2u w; w.x = pk2(v[j][0], v[j][1]); w.y = pk2(v[j][2], v[j][3]); ((GAS v2u*)(Hout + (size_t)r * D))[lane + 64 * j] = w;
;                        v[j] = (f32x4){bflo(w.x), bfhi(w.x), bflo(w.y), bfhi(w.y)}; } }
;         }
;         if (MODE != 2) {
;             float ss = 0.f;
; #pragma unroll
;             for (int j = 0; j < 8; ++j) ss += dot4(v[j], v[j]);
;             ss = wave_sum(ss);
;             const float rs = 1.0f / sqrtf(ss * (1.0f / D) + EPS);
;             float ga[8];
; #pragma unroll
;             for (int c = 0; c < 8; ++c) ga[c] = 0.f;
;             GAS v2u* op = (GAS v2u*)(XN + (size_t)r * D) + lane;
; #pragma unroll
;             for (int j = 0; j < 8; ++j) { const f32x4 g = gpr[j]; const f32x4 xn = (v[j] * rs) * g;
;                 v2u w; w.x = pk2(xn[0], xn[1]); w.y = pk2(xn[2], xn[3]); op[64 * j] = w;
	v_add_f32_e32 v102, v98, v99
	ds_bpermute_b32 v103, v145, v102
	v_lshl_add_u64 v[98:99], v[140:141], 0, s[14:15]
	global_store_dwordx2 v[98:99], v[100:101], off
	v_or_b32_sdwa v100, v91, v124 dst_sel:DWORD dst_unused:UNUSED_PAD src0_sel:DWORD src1_sel:WORD_1
	v_or_b32_sdwa v101, v93, v125 dst_sel:DWORD dst_unused:UNUSED_PAD src0_sel:DWORD src1_sel:WORD_1
	s_waitcnt lgkmcnt(0)
	v_add_f32_e32 v102, v102, v103
	ds_bpermute_b32 v103, v146, v102
	global_store_dwordx2 v[98:99], v[100:101], off offset:512
	v_or_b32_sdwa v100, v83, v114 dst_sel:DWORD dst_unused:UNUSED_PAD src0_sel:DWORD src1_sel:WORD_1
	s_waitcnt lgkmcnt(0)
	v_add_f32_e32 v101, v102, v103
	ds_bpermute_b32 v104, v147, v101
	v_or_b32_sdwa v102, v79, v110 dst_sel:DWORD dst_unused:UNUSED_PAD src0_sel:DWORD src1_sel:WORD_1
	v_or_b32_sdwa v103, v81, v111 dst_sel:DWORD dst_unused:UNUSED_PAD src0_sel:DWORD src1_sel:WORD_1
	global_store_dwordx2 v[98:99], v[102:103], off offset:2048
	v_or_b32_sdwa v102, v71, v112 dst_sel:DWORD dst_unused:UNUSED_PAD src0_sel:DWORD src1_sel:WORD_1
	s_waitcnt lgkmcnt(0)
	v_add_f32_e32 v101, v101, v104
	ds_bpermute_b32 v103, v148, v101
	v_or_b32_sdwa v104, v67, v113 dst_sel:DWORD dst_unused:UNUSED_PAD src0_sel:DWORD src1_sel:WORD_1
	global_store_dwordx2 v[98:99], v[104:105], off offset:3584
	v_or_b32_sdwa v104, v86, v117 dst_sel:DWORD dst_unused:UNUSED_PAD src0_sel:DWORD src1_sel:WORD_1
	v_or_b32_sdwa v105, v87, v116 dst_sel:DWORD dst_unused:UNUSED_PAD src0_sel:DWORD src1_sel:WORD_1
	s_waitcnt lgkmcnt(0)
	v_add_f32_e32 v103, v101, v103
	ds_bpermute_b32 v106, v149, v103
	global_store_dwordx2 v[98:99], v[104:105], off offset:1024
	v_or_b32_sdwa v101, v85, v118 dst_sel:DWORD dst_unused:UNUSED_PAD src0_sel:DWORD src1_sel:WORD_1
	global_store_dwordx2 v[98:99], v[100:101], off offset:1536
	v_or_b32_sdwa v100, v74, v120 dst_sel:DWORD dst_unused:UNUSED_PAD src0_sel:DWORD src1_sel:WORD_1
	s_waitcnt lgkmcnt(0)
	v_add_f32_e32 v103, v103, v106
	v_fmamk_f32 v103, v103, 0x3a000000, v150
	v_mul_f32_e32 v104, 0x4f800000, v103
	v_cmp_gt_f32_e32 vcc, s18, v103
	v_or_b32_sdwa v101, v75, v119 dst_sel:DWORD dst_unused:UNUSED_PAD src0_sel:DWORD src1_sel:WORD_1
	global_store_dwordx2 v[98:99], v[100:101], off offset:2560
	v_cndmask_b32_e32 v103, v103, v104, vcc
	v_sqrt_f32_e32 v104, v103
	s_nop 0
	v_add_u32_e32 v105, -1, v104
	v_fma_f32 v106, -v105, v104, v103
	v_cmp_ge_f32_e64 s[6:7], 0, v106
	v_add_u32_e32 v106, 1, v104
	s_nop 0
	v_cndmask_b32_e64 v105, v104, v105, s[6:7]
	v_fma_f32 v104, -v106, v104, v103
	v_cmp_lt_f32_e64 s[6:7], 0, v104
	s_nop 1
	v_cndmask_b32_e64 v104, v105, v106, s[6:7]
	v_mul_f32_e32 v105, 0x37800000, v104
	v_cndmask_b32_e32 v104, v104, v105, vcc
	v_cmp_class_f32_e32 vcc, v103, v151
	s_nop 1
	v_cndmask_b32_e32 v104, v104, v103, vcc
	v_div_scale_f32 v105, s[6:7], v104, v104, 1.0
	v_rcp_f32_e32 v106, v105
	v_or_b32_sdwa v103, v73, v121 dst_sel:DWORD dst_unused:UNUSED_PAD src0_sel:DWORD src1_sel:WORD_1
	global_store_dwordx2 v[98:99], v[102:103], off offset:3072
	v_fma_f32 v98, -v105, v106, 1.0
	v_fmac_f32_e32 v106, v98, v106
	v_div_scale_f32 v98, vcc, 1.0, v104, 1.0
	v_mul_f32_e32 v99, v98, v106
	v_fma_f32 v100, -v105, v99, v98
	v_fmac_f32_e32 v99, v100, v106
	v_fma_f32 v98, -v105, v99, v98
	v_div_fmas_f32 v98, v98, v106, v99
	v_div_fixup_f32 v98, v98, v104, 1.0
	v_pk_mul_f32 v[94:95], v[98:99], v[94:95] op_sel_hi:[0,1]
	v_pk_mul_f32 v[94:95], v[6:7], v[94:95]
	v_pk_mul_f32 v[96:97], v[98:99], v[96:97] op_sel_hi:[0,1]
	v_bfe_u32 v99, v94, 16, 1
	v_add3_u32 v94, v94, v99, s19
	v_bfe_u32 v99, v95, 16, 1
	v_pk_mul_f32 v[96:97], v[8:9], v[96:97]
	v_lshrrev_b32_e32 v94, 16, v94
	v_add3_u32 v95, v95, v99, s19
	v_and_or_b32 v94, v95, s16, v94
	v_bfe_u32 v95, v96, 16, 1
	v_add3_u32 v95, v96, v95, s19
	v_bfe_u32 v96, v97, 16, 1
	v_lshrrev_b32_e32 v95, 16, v95
	v_add3_u32 v96, v97, v96, s19
	v_pk_mul_f32 v[90:91], v[98:99], v[90:91] op_sel_hi:[0,1]
	v_lshl_add_u64 v[100:101], v[138:139], 0, s[14:15]
	v_and_or_b32 v95, v96, s16, v95
	v_pk_mul_f32 v[90:91], v[14:15], v[90:91]
	global_store_dwordx2 v[100:101], v[94:95], off
	v_bfe_u32 v94, v90, 16, 1
	v_pk_mul_f32 v[92:93], v[98:99], v[92:93] op_sel_hi:[0,1]
	v_add3_u32 v90, v90, v94, s19
	v_bfe_u32 v94, v91, 16, 1
	v_pk_mul_f32 v[92:93], v[16:17], v[92:93]
	v_lshrrev_b32_e32 v90, 16, v90
	v_add3_u32 v91, v91, v94, s19
	v_and_or_b32 v90, v91, s16, v90
	v_bfe_u32 v91, v92, 16, 1
	v_add3_u32 v91, v92, v91, s19
	v_bfe_u32 v92, v93, 16, 1
	v_lshrrev_b32_e32 v91, 16, v91
	v_add3_u32 v92, v93, v92, s19
	v_and_or_b32 v91, v92, s16, v91
	global_store_dwordx2 v[100:101], v[90:91], off offset:512
	v_mov_b32_e32 v90, v88
	v_mov_b32_e32 v91, v86
	v_pk_mul_f32 v[90:91], v[98:99], v[90:91] op_sel_hi:[0,1]
	v_mov_b32_e32 v86, v89
	v_pk_mul_f32 v[88:89], v[22:23], v[90:91]
	v_pk_mul_f32 v[86:87], v[98:99], v[86:87] op_sel_hi:[0,1]
	v_bfe_u32 v90, v88, 16, 1
	v_add3_u32 v88, v88, v90, s19
	v_bfe_u32 v90, v89, 16, 1
	v_pk_mul_f32 v[86:87], v[24:25], v[86:87]
	v_lshrrev_b32_e32 v88, 16, v88
	v_add3_u32 v89, v89, v90, s19
	v_and_or_b32 v88, v89, s16, v88
	v_bfe_u32 v89, v86, 16, 1
	v_add3_u32 v86, v86, v89, s19
	v_bfe_u32 v89, v87, 16, 1
	v_pk_mul_f32 v[82:83], v[98:99], v[82:83] op_sel_hi:[0,1]
	v_lshrrev_b32_e32 v86, 16, v86
	v_add3_u32 v87, v87, v89, s19
; #define GAS __attribute__((address_space(1)))
; __device__ __forceinline__ unsigned pk2(float lo, float hi) { return f2bf(lo) | (f2bf(hi) << 16); }
; __device__ __forceinline__ float bflo(unsigned w) { return __uint_as_float(w << 16); }
; __device__ __forceinline__ float bfhi(unsigned w) { return __uint_as_float(w & 0xffff0000u); }
; __device__ __forceinline__ float sigmf(float x) { return __builtin_amdgcn_rcpf(1.0f + __expf(-x)); }
;     ...
;     for (int r = gw; r < M; r += NGW) {
;         f32x4 v[8];
;         if (RES) { const GAS v2u* rp = (const GAS v2u*)(RES + (size_t)r * D) + lane;
; #pragma unroll
;             for (int j = 0; j < 8; ++j) { const v2u w = rp[64 * j]; v[j] = (f32x4){bflo(w.x), bfhi(w.x), bflo(w.y), bfhi(w.y)}; } }
;         else { const GAS f32x4* rp = (const GAS f32x4*)xrow(a, r) + lane;
; #pragma unroll
;             for (int j = 0; j < 8; ++j) v[j] = rp[64 * j]; }
;         if (MODE != 0) {
;             const GAS v2u* tp = (const GAS v2u*)(T + (size_t)r * D) + lane;
;             f32x4 t[8]; float ss = 0.f;
;             if (TSRC != 0 && r >= NP) {
;                 const GAS f32x4* sp = (const GAS f32x4*)(WSP(float, WS_SLAB) + (size_t)(r - NP) * D) + lane;
; #pragma unroll
;                 for (int j = 0; j < 8; ++j) t[j] = sp[64 * j];
;                 _Pragma("unroll 1") for (int s = 1; s < nslab; ++s) { sp += (size_t)NS * D / 4;
; #pragma unroll
;                     for (int j = 0; j < 8; ++j) t[j] += sp[64 * j]; }
;                 if (TSRC == 2) { const GAS v2u* pp = (const GAS v2u*)(PUP + (size_t)r * D) + lane;
; #pragma unroll
;                     for (int j = 0; j < 8; ++j) { const v2u pw = pp[64 * j]; const f32x4 p = (f32x4){bflo(pw.x), bfhi(pw.x), bflo(pw.y), bfhi(pw.y)}; t[j] = (f32x4){sigmf(t[j][0]), sigmf(t[j][1]), sigmf(t[j][2]), sigmf(t[j][3])} * p; } }
; #pragma unroll
;                 for (int j = 0; j < 8; ++j) ss += dot4(t[j], t[j]);
;             } else {
; #pragma unroll
;                 for (int j = 0; j < 8; ++j) { const v2u tw = tp[64 * j]; t[j] = (f32x4){bflo(tw.x), bfhi(tw.x), bflo(tw.y), bfhi(tw.y)}; ss += dot4(t[j], t[j]); }
;     ...
;             for (int j = 0; j < 8; ++j) { const f32x4 g = gpr[j]; const f32x4 xn = (v[j] * rs) * g;
;                 v2u w; w.x = pk2(xn[0], xn[1]); w.y = pk2(xn[2], xn[3]); op[64 * j] = w;
	v_pk_mul_f32 v[82:83], v[30:31], v[82:83]
	v_and_or_b32 v89, v87, s16, v86
	v_bfe_u32 v86, v82, 16, 1
	v_pk_mul_f32 v[84:85], v[98:99], v[84:85] op_sel_hi:[0,1]
	v_add3_u32 v82, v82, v86, s19
	v_bfe_u32 v86, v83, 16, 1
	v_pk_mul_f32 v[84:85], v[32:33], v[84:85]
	v_lshrrev_b32_e32 v82, 16, v82
	v_add3_u32 v83, v83, v86, s19
	v_and_or_b32 v82, v83, s16, v82
	v_bfe_u32 v83, v84, 16, 1
	v_add3_u32 v83, v84, v83, s19
	v_bfe_u32 v84, v85, 16, 1
	v_lshrrev_b32_e32 v83, 16, v83
	v_add3_u32 v84, v85, v84, s19
	v_pk_mul_f32 v[78:79], v[98:99], v[78:79] op_sel_hi:[0,1]
	v_and_or_b32 v83, v84, s16, v83
	v_pk_mul_f32 v[78:79], v[38:39], v[78:79]
	global_store_dwordx2 v[100:101], v[82:83], off offset:1536
	v_bfe_u32 v82, v78, 16, 1
	v_pk_mul_f32 v[80:81], v[98:99], v[80:81] op_sel_hi:[0,1]
	v_add3_u32 v78, v78, v82, s19
	v_bfe_u32 v82, v79, 16, 1
	v_pk_mul_f32 v[80:81], v[40:41], v[80:81]
	v_lshrrev_b32_e32 v78, 16, v78
	v_add3_u32 v79, v79, v82, s19
	v_and_or_b32 v78, v79, s16, v78
	v_bfe_u32 v79, v80, 16, 1
	v_add3_u32 v79, v80, v79, s19
	v_bfe_u32 v80, v81, 16, 1
	v_lshrrev_b32_e32 v79, 16, v79
	v_add3_u32 v80, v81, v80, s19
	v_and_or_b32 v79, v80, s16, v79
	global_store_dwordx2 v[100:101], v[78:79], off offset:2048
	v_mov_b32_e32 v78, v76
	v_mov_b32_e32 v79, v74
	v_pk_mul_f32 v[78:79], v[98:99], v[78:79] op_sel_hi:[0,1]
	v_mov_b32_e32 v74, v77
	v_pk_mul_f32 v[76:77], v[46:47], v[78:79]
	v_pk_mul_f32 v[74:75], v[98:99], v[74:75] op_sel_hi:[0,1]
	v_bfe_u32 v78, v76, 16, 1
	v_add3_u32 v76, v76, v78, s19
	v_bfe_u32 v78, v77, 16, 1
	v_pk_mul_f32 v[74:75], v[48:49], v[74:75]
	v_lshrrev_b32_e32 v76, 16, v76
	v_add3_u32 v77, v77, v78, s19
	v_and_or_b32 v76, v77, s16, v76
	v_bfe_u32 v77, v74, 16, 1
	v_add3_u32 v74, v74, v77, s19
	v_bfe_u32 v77, v75, 16, 1
	v_pk_mul_f32 v[70:71], v[98:99], v[70:71] op_sel_hi:[0,1]
	v_lshrrev_b32_e32 v74, 16, v74
	v_add3_u32 v75, v75, v77, s19
	v_pk_mul_f32 v[70:71], v[54:55], v[70:71]
	v_and_or_b32 v77, v75, s16, v74
	v_bfe_u32 v74, v70, 16, 1
	v_pk_mul_f32 v[72:73], v[98:99], v[72:73] op_sel_hi:[0,1]
	v_add3_u32 v70, v70, v74, s19
	v_bfe_u32 v74, v71, 16, 1
	v_pk_mul_f32 v[72:73], v[56:57], v[72:73]
	v_lshrrev_b32_e32 v70, 16, v70
	v_add3_u32 v71, v71, v74, s19
	v_and_or_b32 v70, v71, s16, v70
	v_bfe_u32 v71, v72, 16, 1
	v_add3_u32 v71, v72, v71, s19
	v_bfe_u32 v72, v73, 16, 1
	v_lshrrev_b32_e32 v71, 16, v71
	v_add3_u32 v72, v73, v72, s19
	v_pk_mul_f32 v[66:67], v[98:99], v[66:67] op_sel_hi:[0,1]
	v_and_or_b32 v71, v72, s16, v71
	v_pk_mul_f32 v[66:67], v[62:63], v[66:67]
	global_store_dwordx2 v[100:101], v[70:71], off offset:3072
	v_bfe_u32 v70, v66, 16, 1
	v_pk_mul_f32 v[68:69], v[98:99], v[68:69] op_sel_hi:[0,1]
	v_add3_u32 v66, v66, v70, s19
	v_bfe_u32 v70, v67, 16, 1
	v_pk_mul_f32 v[68:69], v[64:65], v[68:69]
	v_lshrrev_b32_e32 v66, 16, v66
	v_add3_u32 v67, v67, v70, s19
	v_and_or_b32 v66, v67, s16, v66
	v_bfe_u32 v67, v68, 16, 1
	v_add3_u32 v67, v68, v67, s19
	v_bfe_u32 v68, v69, 16, 1
	v_lshrrev_b32_e32 v67, 16, v67
	v_add3_u32 v68, v69, v68, s19
	v_and_or_b32 v67, v68, s16, v67
	global_store_dwordx2 v[100:101], v[88:89], off offset:1024
	global_store_dwordx2 v[100:101], v[76:77], off offset:2560
	global_store_dwordx2 v[100:101], v[66:67], off offset:3584
	s_cbranch_scc0 .LBB0_278
.LBB0_272:
	s_cmp_lt_i32 s8, s3
	s_cbranch_scc1 .Lrowpf272_orig
	s_cmpk_gt_i32 s8, 0x1fff
	s_cbranch_scc1 .Lrowpf272_orig
	s_waitcnt vmcnt(16)
	s_add_i32 s10, s8, 0xffffe000
	s_ashr_i32 s9, s8, 31
	s_cmpk_lt_i32 s8, 0x2000
	s_cselect_b32 s7, s9, 0
	s_cselect_b32 s6, s8, s10
	s_waitcnt lgkmcnt(0)
	s_cselect_b32 s13, s37, s39
	s_cselect_b32 s14, s36, s38
	s_lshl_b64 s[6:7], s[6:7], 13
	s_add_u32 s6, s14, s6
	s_addc_u32 s7, s13, s7
	v_lshl_add_u64 v[66:67], s[6:7], 0, v[130:131]
	v_add_co_u32_e32 v66, vcc, 0x1000, v66
	v_mov_b32_e32 v94, v186
	v_mov_b32_e32 v95, v187
	v_mov_b32_e32 v96, v188
	v_mov_b32_e32 v97, v189
	v_mov_b32_e32 v90, v190
	v_mov_b32_e32 v91, v191
	v_mov_b32_e32 v92, v192
	v_mov_b32_e32 v93, v193
	v_mov_b32_e32 v86, v194
	v_mov_b32_e32 v87, v195
	v_mov_b32_e32 v88, v196
	v_mov_b32_e32 v89, v197
	v_mov_b32_e32 v82, v198
	v_mov_b32_e32 v83, v199
	v_mov_b32_e32 v84, v200
	v_mov_b32_e32 v85, v201
	v_addc_co_u32_e32 v67, vcc, 0, v67, vcc
	v_mov_b32_e32 v78, v202
	v_mov_b32_e32 v79, v203
	v_mov_b32_e32 v80, v204
	v_mov_b32_e32 v81, v205
	v_mov_b32_e32 v74, v206
	v_mov_b32_e32 v75, v207
	v_mov_b32_e32 v76, v208
	v_mov_b32_e32 v77, v209
	v_mov_b32_e32 v70, v210
	v_mov_b32_e32 v71, v211
	v_mov_b32_e32 v72, v212
	v_mov_b32_e32 v73, v213
	s_nop 0
	v_mov_b32_e32 v66, v214
	v_mov_b32_e32 v67, v215
	v_mov_b32_e32 v68, v216
	v_mov_b32_e32 v69, v217
	s_lshl_b64 s[14:15], s[8:9], 11
	s_cmpk_gt_i32 s8, 0x1fff
	s_mov_b64 s[6:7], -1
	v_lshl_add_u64 v[98:99], s[14:15], 1, v[132:133]
	v_mov_b32_e32 v100, v218
	v_mov_b32_e32 v101, v219
	v_mov_b32_e32 v102, v220
	v_mov_b32_e32 v103, v221
	v_mov_b32_e32 v104, v222
	v_mov_b32_e32 v105, v223
	v_mov_b32_e32 v106, v224
	v_mov_b32_e32 v107, v225
	v_mov_b32_e32 v108, v226
	v_mov_b32_e32 v109, v227
	v_mov_b32_e32 v118, v228
	v_mov_b32_e32 v119, v229
	v_mov_b32_e32 v120, v230
	v_mov_b32_e32 v121, v231
	v_mov_b32_e32 v126, v232
	v_mov_b32_e32 v127, v233
	s_mov_b64 s[6:7], 0
	s_branch .Lrowpf272_conv

; #define GAS __attribute__((address_space(1)))
; __device__ __forceinline__ float bflo(unsigned w) { return __uint_as_float(w << 16); }
; __device__ __forceinline__ float bfhi(unsigned w) { return __uint_as_float(w & 0xffff0000u); }
; __device__ __forceinline__ float sigmf(float x) { return __builtin_amdgcn_rcpf(1.0f + __expf(-x)); }
; __device__ __forceinline__ float dot4(f32x4 a, f32x4 b) { return (a[0] * b[0] + a[1] * b[1]) + (a[2] * b[2] + a[3] * b[3]); }
;     ...
;             const GAS v2u* tp = (const GAS v2u*)(T + (size_t)r * D) + lane;
;             f32x4 t[8]; float ss = 0.f;
;             if (TSRC != 0 && r >= NP) {
;                 const GAS f32x4* sp = (const GAS f32x4*)(WSP(float, WS_SLAB) + (size_t)(r - NP) * D) + lane;
; #pragma unroll
;                 for (int j = 0; j < 8; ++j) t[j] = sp[64 * j];
;                 _Pragma("unroll 1") for (int s = 1; s < nslab; ++s) { sp += (size_t)NS * D / 4;
; #pragma unroll
;                     for (int j = 0; j < 8; ++j) t[j] += sp[64 * j]; }
;                 if (TSRC == 2) { const GAS v2u* pp = (const GAS v2u*)(PUP + (size_t)r * D) + lane;
; #pragma unroll
;                     for (int j = 0; j < 8; ++j) { const v2u pw = pp[64 * j]; const f32x4 p = (f32x4){bflo(pw.x), bfhi(pw.x), bflo(pw.y), bfhi(pw.y)}; t[j] = (f32x4){sigmf(t[j][0]), sigmf(t[j][1]), sigmf(t[j][2]), sigmf(t[j][3])} * p; } }
; #pragma unroll
;                 for (int j = 0; j < 8; ++j) ss += dot4(t[j], t[j]);
;             } else {
; #pragma unroll
;                 for (int j = 0; j < 8; ++j) { const v2u tw = tp[64 * j]; t[j] = (f32x4){bflo(tw.x), bfhi(tw.x), bflo(tw.y), bfhi(tw.y)}; ss += dot4(t[j], t[j]); }
.Lrowpf272_conv:
	v_and_b32_e32 v123, 0xffff0000, v100
	v_and_b32_e32 v125, 0xffff0000, v101
	v_and_b32_e32 v155, 0xffff0000, v103
	v_and_b32_e32 v154, 0xffff0000, v102
	v_lshlrev_b32_e32 v110, 16, v106
	v_lshlrev_b32_e32 v122, 16, v100
	v_lshlrev_b32_e32 v124, 16, v101
	v_lshlrev_b32_e32 v143, 16, v103
	v_lshlrev_b32_e32 v142, 16, v102
	v_lshlrev_b32_e32 v100, 16, v127
	v_and_b32_e32 v101, 0xffff0000, v127
	v_mul_f32_e32 v162, v125, v125
	v_mov_b32_e32 v127, v154
	v_mov_b32_e32 v129, v155
	v_pk_mul_f32 v[154:155], v[154:155], v[154:155]
	v_mul_f32_e32 v164, v123, v123
	v_mov_b32_e32 v163, v110
	v_mov_b32_e32 v165, v110
	v_and_b32_e32 v115, 0xffff0000, v104
	v_and_b32_e32 v117, 0xffff0000, v105
	v_and_b32_e32 v111, 0xffff0000, v106
	v_lshlrev_b32_e32 v112, 16, v107
	v_and_b32_e32 v113, 0xffff0000, v107
	v_and_b32_e32 v107, 0xffff0000, v109
	v_and_b32_e32 v106, 0xffff0000, v108
	v_and_b32_e32 v161, 0xffff0000, v119
	v_and_b32_e32 v160, 0xffff0000, v118
	v_lshlrev_b32_e32 v98, 16, v126
	v_and_b32_e32 v99, 0xffff0000, v126
	v_mov_b32_e32 v126, v142
	v_mov_b32_e32 v128, v143
	v_pk_fma_f32 v[172:173], v[124:125], v[124:125], v[162:163] op_sel_hi:[1,1,0]
	v_pk_fma_f32 v[142:143], v[142:143], v[142:143], v[154:155]
	v_pk_fma_f32 v[154:155], v[122:123], v[122:123], v[164:165] op_sel_hi:[1,1,0]
	v_lshlrev_b32_e32 v114, 16, v104
	v_lshlrev_b32_e32 v116, 16, v105
	v_lshlrev_b32_e32 v157, 16, v109
	v_lshlrev_b32_e32 v159, 16, v119
	v_lshlrev_b32_e32 v158, 16, v118
	v_lshlrev_b32_e32 v104, 16, v121
	v_and_b32_e32 v105, 0xffff0000, v121
	v_mul_f32_e32 v166, v115, v115
	v_mul_f32_e32 v168, v117, v117
	v_mov_b32_e32 v121, v107
	v_pk_mul_f32 v[170:171], v[106:107], v[106:107]
	v_mov_b32_e32 v107, v160
	v_mov_b32_e32 v109, v161
	v_pk_mul_f32 v[160:161], v[160:161], v[160:161]
	v_mov_b32_e32 v167, v98
	v_mov_b32_e32 v162, v154
	v_mov_b32_e32 v164, v172
	v_lshlrev_b32_e32 v156, 16, v108
	v_mul_f32_e32 v153, v111, v111
	v_mul_f32_e32 v176, v112, v112
	v_mul_f32_e32 v177, v113, v113
	v_mov_b32_e32 v119, v106
	v_mov_b32_e32 v106, v158
	v_mov_b32_e32 v108, v159
	v_pk_fma_f32 v[174:175], v[114:115], v[114:115], v[166:167] op_sel_hi:[1,1,0]
	v_pk_fma_f32 v[168:169], v[116:117], v[116:117], v[168:169] op_sel_hi:[1,1,0]
	v_pk_fma_f32 v[158:159], v[158:159], v[158:159], v[160:161]
	v_pk_add_f32 v[154:155], v[154:155], v[172:173]
	v_pk_add_f32 v[142:143], v[142:143], v[142:143] op_sel:[0,1] op_sel_hi:[1,0]
	v_pk_mul_f32 v[160:161], v[162:163], v[164:165]
	v_mov_b32_e32 v175, v176
	v_mov_b32_e32 v169, v177
	v_mov_b32_e32 v143, v153
	v_mov_b32_e32 v155, v161
	v_pk_add_f32 v[162:163], v[174:175], v[168:169]
	v_pk_add_f32 v[142:143], v[154:155], v[142:143]
	v_lshlrev_b32_e32 v102, 16, v120
	v_and_b32_e32 v103, 0xffff0000, v120
	v_mov_b32_e32 v118, v156
	v_mov_b32_e32 v120, v157
	v_pk_fma_f32 v[156:157], v[156:157], v[156:157], v[170:171]
	v_pk_add_f32 v[142:143], v[142:143], v[162:163]
	v_pk_add_f32 v[156:157], v[156:157], v[156:157] op_sel:[0,1] op_sel_hi:[1,0]
	v_pk_add_f32 v[142:143], v[142:143], v[142:143] op_sel:[0,1] op_sel_hi:[1,0]
	v_mov_b32_e32 v154, v156
	v_mov_b32_e32 v166, v142
	v_mov_b32_e32 v155, v98
	v_pk_add_f32 v[142:143], v[142:143], v[156:157]
	v_pk_mul_f32 v[154:155], v[166:167], v[154:155]
	v_mul_f32_e32 v178, v99, v99
	v_mov_b32_e32 v143, v155
	v_pk_add_f32 v[154:155], v[158:159], v[158:159] op_sel:[0,1] op_sel_hi:[1,0]
	v_mul_f32_e32 v156, v105, v105
	v_mov_b32_e32 v155, v178
	v_pk_add_f32 v[142:143], v[142:143], v[154:155]
	v_mul_f32_e32 v154, v103, v103
	v_mul_f32_e32 v179, v100, v100
	v_mul_f32_e32 v180, v101, v101
	v_pk_fma_f32 v[154:155], v[102:103], v[102:103], v[154:155] op_sel_hi:[1,1,0]
	v_pk_fma_f32 v[156:157], v[104:105], v[104:105], v[156:157] op_sel_hi:[1,1,0]
	v_mov_b32_e32 v155, v179
	v_mov_b32_e32 v157, v180
	v_pk_add_f32 v[154:155], v[154:155], v[156:157]
	s_nop 0
	v_pk_add_f32 v[142:143], v[142:143], v[154:155]
	s_nop 0
	v_add_f32_e32 v142, v142, v143

; #define GAS __attribute__((address_space(1)))
; __device__ __forceinline__ unsigned pk2(float lo, float hi) { return f2bf(lo) | (f2bf(hi) << 16); }
;     ...
;     for (int r = gw; r < M; r += NGW) {
;         f32x4 v[8];
;         if (RES) { const GAS v2u* rp = (const GAS v2u*)(RES + (size_t)r * D) + lane;
; #pragma unroll
;             for (int j = 0; j < 8; ++j) { const v2u w = rp[64 * j]; v[j] = (f32x4){bflo(w.x), bfhi(w.x), bflo(w.y), bfhi(w.y)}; } }
;         else { const GAS f32x4* rp = (const GAS f32x4*)xrow(a, r) + lane;
; #pragma unroll
;             for (int j = 0; j < 8; ++j) v[j] = rp[64 * j]; }
;         if (MODE != 0) {
;             const GAS v2u* tp = (const GAS v2u*)(T + (size_t)r * D) + lane;
;             f32x4 t[8]; float ss = 0.f;
;             if (TSRC != 0 && r >= NP) {
;                 const GAS f32x4* sp = (const GAS f32x4*)(WSP(float, WS_SLAB) + (size_t)(r - NP) * D) + lane;
; #pragma unroll
;                 for (int j = 0; j < 8; ++j) t[j] = sp[64 * j];
;                 _Pragma("unroll 1") for (int s = 1; s < nslab; ++s) { sp += (size_t)NS * D / 4;
; #pragma unroll
;                     for (int j = 0; j < 8; ++j) t[j] += sp[64 * j]; }
;                 if (TSRC == 2) { const GAS v2u* pp = (const GAS v2u*)(PUP + (size_t)r * D) + lane;
; #pragma unroll
;                     for (int j = 0; j < 8; ++j) { const v2u pw = pp[64 * j]; const f32x4 p = (f32x4){bflo(pw.x), bfhi(pw.x), bflo(pw.y), bfhi(pw.y)}; t[j] = (f32x4){sigmf(t[j][0]), sigmf(t[j][1]), sigmf(t[j][2]), sigmf(t[j][3])} * p; } }
; #pragma unroll
;                 for (int j = 0; j < 8; ++j) ss += dot4(t[j], t[j]);
;             } else {
; #pragma unroll
;                 for (int j = 0; j < 8; ++j) { const v2u tw = tp[64 * j]; t[j] = (f32x4){bflo(tw.x), bfhi(tw.x), bflo(tw.y), bfhi(tw.y)}; ss += dot4(t[j], t[j]); }
;             }
;             ss = wave_sum(ss);
;             const float rs = sc * (1.0f / sqrtf(ss * (1.0f / D) + EPS));
; #pragma unroll
;             for (int j = 0; j < 8; ++j) { const f32x4 g = gpo[j]; v[j] = v[j] + (t[j] * rs) * g;
;                 if (MODE == 2) ((GAS f32x4*)(Yout + (size_t)r * D))[lane + 64 * j] = v[j];
;                 else { v2u w; w.x = pk2(v[j][0], v[j][1]); w.y = pk2(v[j][2], v[j][3]); ((GAS v2u*)(Hout + (size_t)r * D))[lane + 64 * j] = w;
;                        v[j] = (f32x4){bflo(w.x), bfhi(w.x), bflo(w.y), bfhi(w.y)}; } }
.LBB0_1486:
	ds_bpermute_b32 v125, v126, v124
	s_add_i32 s36, s8, s3
	s_cmpk_gt_i32 s36, 0x1fff
	s_cbranch_scc1 .Lrowpf1487_skip
	s_lshl_b32 s36, s36, 12
	s_mov_b32 s37, 0
	v_lshl_add_u64 v[200:201], v[98:99], 0, s[36:37]
	global_load_dwordx2 v[168:169], v[200:201], off
	global_load_dwordx2 v[170:171], v[200:201], off offset:512
	global_load_dwordx2 v[172:173], v[200:201], off offset:1024
	global_load_dwordx2 v[174:175], v[200:201], off offset:1536
	global_load_dwordx2 v[176:177], v[200:201], off offset:2048
	global_load_dwordx2 v[178:179], v[200:201], off offset:2560
	global_load_dwordx2 v[180:181], v[200:201], off offset:3072
	global_load_dwordx2 v[182:183], v[200:201], off offset:3584
	s_nop 0
	v_lshl_add_u64 v[200:201], v[100:101], 0, s[36:37]
	global_load_dwordx2 v[184:185], v[200:201], off
	global_load_dwordx2 v[186:187], v[200:201], off offset:512
	global_load_dwordx2 v[188:189], v[200:201], off offset:1024
	global_load_dwordx2 v[190:191], v[200:201], off offset:1536
	global_load_dwordx2 v[192:193], v[200:201], off offset:2048
	global_load_dwordx2 v[194:195], v[200:201], off offset:2560
	global_load_dwordx2 v[196:197], v[200:201], off offset:3072
	global_load_dwordx2 v[198:199], v[200:201], off offset:3584
.Lrowpf1487_skip:
	v_and_b32_e32 v147, 0xffff0000, v110
	v_and_b32_e32 v149, 0xffff0000, v111
	v_lshlrev_b32_e32 v136, 16, v122
	v_and_b32_e32 v137, 0xffff0000, v122
	s_waitcnt lgkmcnt(0)
	v_add_f32_e32 v135, v124, v125
	ds_bpermute_b32 v140, v127, v135
	v_lshlrev_b32_e32 v138, 16, v120
	v_and_b32_e32 v139, 0xffff0000, v120
	v_and_b32_e32 v145, 0xffff0000, v112
	v_lshlrev_b32_e32 v122, 16, v123
	s_waitcnt lgkmcnt(0)
	v_add_f32_e32 v135, v135, v140
	ds_bpermute_b32 v142, v128, v135
	v_and_b32_e32 v123, 0xffff0000, v123
	v_lshlrev_b32_e32 v120, 16, v121
	v_and_b32_e32 v121, 0xffff0000, v121
	v_lshlrev_b32_e32 v140, 16, v116
	s_waitcnt lgkmcnt(0)
	v_add_f32_e32 v135, v135, v142
	ds_bpermute_b32 v144, v129, v135
	v_and_b32_e32 v141, 0xffff0000, v116
	v_lshlrev_b32_e32 v124, 16, v118
	v_and_b32_e32 v125, 0xffff0000, v118
	v_lshlrev_b32_e32 v142, 16, v114
	s_waitcnt lgkmcnt(0)
	v_add_f32_e32 v135, v135, v144
	ds_bpermute_b32 v146, v130, v135
	v_lshlrev_b32_e32 v144, 16, v112
	v_lshlrev_b32_e32 v112, 16, v113
	v_and_b32_e32 v113, 0xffff0000, v113
	v_and_b32_e32 v143, 0xffff0000, v114
	s_waitcnt lgkmcnt(0)
	v_add_f32_e32 v135, v135, v146
	ds_bpermute_b32 v148, v131, v135
	v_lshlrev_b32_e32 v146, 16, v110
	v_lshlrev_b32_e32 v118, 16, v119
	v_and_b32_e32 v119, 0xffff0000, v119
	v_lshlrev_b32_e32 v116, 16, v117
	s_waitcnt lgkmcnt(0)
	v_add_f32_e32 v110, v135, v148
	v_fmamk_f32 v110, v110, 0x3a000000, v132
	v_mul_f32_e32 v135, 0x4f800000, v110
	v_cmp_gt_f32_e32 vcc, s18, v110
	v_lshlrev_b32_e32 v148, 16, v111
	v_and_b32_e32 v117, 0xffff0000, v117
	v_cndmask_b32_e32 v135, v110, v135, vcc
	v_sqrt_f32_e32 v150, v135
	v_lshlrev_b32_e32 v110, 16, v108
	v_lshlrev_b32_e32 v114, 16, v115
	v_and_b32_e32 v115, 0xffff0000, v115
	v_add_u32_e32 v111, -1, v150
	v_fma_f32 v151, -v111, v150, v135
	v_cmp_ge_f32_e64 s[0:1], 0, v151
	v_add_u32_e32 v151, 1, v150
	s_lshl_b64 s[12:13], s[12:13], 1
	v_cndmask_b32_e64 v111, v150, v111, s[0:1]
	v_fma_f32 v150, -v151, v150, v135
	v_cmp_lt_f32_e64 s[0:1], 0, v150
	s_add_i32 s8, s8, s3
	s_add_i32 s10, s10, s3
	v_cndmask_b32_e64 v111, v111, v151, s[0:1]
	v_mul_f32_e32 v150, 0x37800000, v111
	v_cndmask_b32_e32 v111, v111, v150, vcc
	v_cmp_class_f32_e32 vcc, v135, v133
	s_cmpk_lt_i32 s8, 0x2200
	s_nop 0
	v_cndmask_b32_e32 v135, v111, v135, vcc
	v_div_scale_f32 v150, s[0:1], v135, v135, 1.0
	v_rcp_f32_e32 v151, v150
	v_and_b32_e32 v111, 0xffff0000, v108
	v_lshlrev_b32_e32 v108, 16, v109
	v_and_b32_e32 v109, 0xffff0000, v109
	v_fma_f32 v152, -v150, v151, 1.0
	v_fmac_f32_e32 v151, v152, v151
	v_div_scale_f32 v152, vcc, 1.0, v135, 1.0
	v_mul_f32_e32 v153, v152, v151
	v_fma_f32 v154, -v150, v153, v152
	v_fmac_f32_e32 v153, v154, v151
	v_fma_f32 v150, -v150, v153, v152
	v_div_fmas_f32 v150, v150, v151, v153
	v_div_fixup_f32 v150, v150, v135, 1.0
	v_pk_mul_f32 v[90:91], v[90:91], v[150:151] op_sel_hi:[1,0]
	v_pk_mul_f32 v[94:95], v[94:95], v[150:151] op_sel_hi:[1,0]
	v_pk_mul_f32 v[74:75], v[74:75], v[150:151] op_sel_hi:[1,0]
	v_pk_mul_f32 v[92:93], v[92:93], v[150:151] op_sel_hi:[1,0]
	v_pk_fma_f32 v[90:91], v[2:3], v[90:91], v[136:137]
	v_pk_mul_f32 v[96:97], v[96:97], v[150:151] op_sel_hi:[1,0]
	v_pk_fma_f32 v[94:95], v[10:11], v[94:95], v[138:139]
	v_pk_mul_f32 v[76:77], v[76:77], v[150:151] op_sel_hi:[1,0]
	v_pk_fma_f32 v[74:75], v[42:43], v[74:75], v[144:145]
	v_pk_fma_f32 v[92:93], v[4:5], v[92:93], v[122:123]
	v_and_b32_sdwa v122, v91, v134 dst_sel:DWORD dst_unused:UNUSED_PAD src0_sel:WORD_1 src1_sel:DWORD
	v_and_b32_sdwa v123, v90, v134 dst_sel:DWORD dst_unused:UNUSED_PAD src0_sel:WORD_1 src1_sel:DWORD
	v_pk_fma_f32 v[96:97], v[12:13], v[96:97], v[120:121]
	v_and_b32_sdwa v120, v95, v134 dst_sel:DWORD dst_unused:UNUSED_PAD src0_sel:WORD_1 src1_sel:DWORD
	v_and_b32_sdwa v121, v94, v134 dst_sel:DWORD dst_unused:UNUSED_PAD src0_sel:WORD_1 src1_sel:DWORD
	v_pk_fma_f32 v[76:77], v[44:45], v[76:77], v[112:113]
	v_and_b32_sdwa v112, v75, v134 dst_sel:DWORD dst_unused:UNUSED_PAD src0_sel:WORD_1 src1_sel:DWORD
	v_and_b32_sdwa v113, v74, v134 dst_sel:DWORD dst_unused:UNUSED_PAD src0_sel:WORD_1 src1_sel:DWORD
	v_pk_mul_f32 v[70:71], v[70:71], v[150:151] op_sel_hi:[1,0]
	v_pk_mul_f32 v[66:67], v[66:67], v[150:151] op_sel_hi:[1,0]
	v_add3_u32 v91, v91, v122, s19
	v_add3_u32 v122, v90, v123, s19
	v_and_b32_sdwa v123, v93, v134 dst_sel:DWORD dst_unused:UNUSED_PAD src0_sel:WORD_1 src1_sel:DWORD
; #define GAS __attribute__((address_space(1)))
; __device__ __forceinline__ unsigned pk2(float lo, float hi) { return f2bf(lo) | (f2bf(hi) << 16); }
; __device__ __forceinline__ float bflo(unsigned w) { return __uint_as_float(w << 16); }
; __device__ __forceinline__ float bfhi(unsigned w) { return __uint_as_float(w & 0xffff0000u); }
; __device__ __forceinline__ float dot4(f32x4 a, f32x4 b) { return (a[0] * b[0] + a[1] * b[1]) + (a[2] * b[2] + a[3] * b[3]); }
;     ...
;             for (int j = 0; j < 8; ++j) { const f32x4 g = gpo[j]; v[j] = v[j] + (t[j] * rs) * g;
;                 if (MODE == 2) ((GAS f32x4*)(Yout + (size_t)r * D))[lane + 64 * j] = v[j];
;                 else { v2u w; w.x = pk2(v[j][0], v[j][1]); w.y = pk2(v[j][2], v[j][3]); ((GAS v2u*)(Hout + (size_t)r * D))[lane + 64 * j] = w;
;                        v[j] = (f32x4){bflo(w.x), bfhi(w.x), bflo(w.y), bfhi(w.y)}; } }
;         }
;         if (MODE != 2) {
;             float ss = 0.f;
; #pragma unroll
;             for (int j = 0; j < 8; ++j) ss += dot4(v[j], v[j]);
;             ss = wave_sum(ss);
	v_and_b32_sdwa v135, v92, v134 dst_sel:DWORD dst_unused:UNUSED_PAD src0_sel:WORD_1 src1_sel:DWORD
	v_add3_u32 v95, v95, v120, s19
	v_add3_u32 v120, v94, v121, s19
	v_and_b32_sdwa v121, v97, v134 dst_sel:DWORD dst_unused:UNUSED_PAD src0_sel:WORD_1 src1_sel:DWORD
	v_pk_mul_f32 v[78:79], v[78:79], v[150:151] op_sel_hi:[1,0]
	v_add3_u32 v75, v75, v112, s19
	v_add3_u32 v139, v74, v113, s19
	v_and_b32_sdwa v112, v77, v134 dst_sel:DWORD dst_unused:UNUSED_PAD src0_sel:WORD_1 src1_sel:DWORD
	v_and_b32_sdwa v113, v76, v134 dst_sel:DWORD dst_unused:UNUSED_PAD src0_sel:WORD_1 src1_sel:DWORD
	v_pk_mul_f32 v[72:73], v[72:73], v[150:151] op_sel_hi:[1,0]
	v_pk_fma_f32 v[70:71], v[50:51], v[70:71], v[146:147]
	v_pk_mul_f32 v[68:69], v[68:69], v[150:151] op_sel_hi:[1,0]
	v_pk_fma_f32 v[66:67], v[58:59], v[66:67], v[110:111]
	v_and_b32_e32 v91, 0xffff0000, v91
	v_add3_u32 v93, v93, v123, s19
	v_add3_u32 v123, v92, v135, s19
	v_and_b32_e32 v95, 0xffff0000, v95
	v_and_b32_sdwa v135, v96, v134 dst_sel:DWORD dst_unused:UNUSED_PAD src0_sel:WORD_1 src1_sel:DWORD
	v_add3_u32 v97, v97, v121, s19
	v_pk_mul_f32 v[86:87], v[86:87], v[150:151] op_sel_hi:[1,0]
	v_pk_fma_f32 v[78:79], v[26:27], v[78:79], v[140:141]
	v_pk_mul_f32 v[82:83], v[82:83], v[150:151] op_sel_hi:[1,0]
	v_add3_u32 v77, v77, v112, s19
	v_add3_u32 v140, v76, v113, s19
	v_pk_fma_f32 v[72:73], v[52:53], v[72:73], v[148:149]
	v_and_b32_sdwa v112, v71, v134 dst_sel:DWORD dst_unused:UNUSED_PAD src0_sel:WORD_1 src1_sel:DWORD
	v_and_b32_sdwa v113, v70, v134 dst_sel:DWORD dst_unused:UNUSED_PAD src0_sel:WORD_1 src1_sel:DWORD
	v_pk_fma_f32 v[68:69], v[60:61], v[68:69], v[108:109]
	v_and_b32_sdwa v108, v67, v134 dst_sel:DWORD dst_unused:UNUSED_PAD src0_sel:WORD_1 src1_sel:DWORD
	v_and_b32_sdwa v109, v66, v134 dst_sel:DWORD dst_unused:UNUSED_PAD src0_sel:WORD_1 src1_sel:DWORD
	v_and_b32_e32 v90, 0xffff0000, v122
	v_and_b32_e32 v93, 0xffff0000, v93
	v_and_b32_e32 v94, 0xffff0000, v120
	v_add3_u32 v121, v96, v135, s19
	v_and_b32_e32 v97, 0xffff0000, v97
	v_pk_mul_f32 v[88:89], v[88:89], v[150:151] op_sel_hi:[1,0]
	v_pk_fma_f32 v[86:87], v[18:19], v[86:87], v[124:125]
	v_pk_fma_f32 v[82:83], v[34:35], v[82:83], v[142:143]
	v_add3_u32 v71, v71, v112, s19
	v_add3_u32 v141, v70, v113, s19
	v_and_b32_sdwa v112, v73, v134 dst_sel:DWORD dst_unused:UNUSED_PAD src0_sel:WORD_1 src1_sel:DWORD
	v_and_b32_sdwa v113, v72, v134 dst_sel:DWORD dst_unused:UNUSED_PAD src0_sel:WORD_1 src1_sel:DWORD
	v_add3_u32 v67, v67, v108, s19
	v_add3_u32 v143, v66, v109, s19
	v_and_b32_sdwa v108, v69, v134 dst_sel:DWORD dst_unused:UNUSED_PAD src0_sel:WORD_1 src1_sel:DWORD
	v_and_b32_sdwa v109, v68, v134 dst_sel:DWORD dst_unused:UNUSED_PAD src0_sel:WORD_1 src1_sel:DWORD
	v_mov_b32_e32 v110, v91
	v_mov_b32_e32 v111, v95
	v_and_b32_e32 v92, 0xffff0000, v123
	v_and_b32_e32 v96, 0xffff0000, v121
	v_pk_fma_f32 v[88:89], v[20:21], v[88:89], v[118:119]
	v_and_b32_sdwa v118, v87, v134 dst_sel:DWORD dst_unused:UNUSED_PAD src0_sel:WORD_1 src1_sel:DWORD
	v_add3_u32 v73, v73, v112, s19
	v_add3_u32 v142, v72, v113, s19
	v_add3_u32 v69, v69, v108, s19
	v_add3_u32 v144, v68, v109, s19
	v_mov_b32_e32 v108, v90
	v_mov_b32_e32 v109, v94
	v_pk_mul_f32 v[110:111], v[110:111], v[110:111]
	v_mov_b32_e32 v112, v93
	v_mov_b32_e32 v113, v97
	v_and_b32_sdwa v119, v86, v134 dst_sel:DWORD dst_unused:UNUSED_PAD src0_sel:WORD_1 src1_sel:DWORD
	v_add3_u32 v87, v87, v118, s19
	v_and_b32_sdwa v118, v89, v134 dst_sel:DWORD dst_unused:UNUSED_PAD src0_sel:WORD_1 src1_sel:DWORD
	v_pk_mul_f32 v[80:81], v[80:81], v[150:151] op_sel_hi:[1,0]
	v_pk_fma_f32 v[108:109], v[108:109], v[108:109], v[110:111]
	v_mov_b32_e32 v110, v92
	v_mov_b32_e32 v111, v96
	v_pk_mul_f32 v[112:113], v[112:113], v[112:113]
	v_add3_u32 v124, v86, v119, s19
	v_and_b32_sdwa v119, v88, v134 dst_sel:DWORD dst_unused:UNUSED_PAD src0_sel:WORD_1 src1_sel:DWORD
	v_add3_u32 v89, v89, v118, s19
	v_pk_fma_f32 v[80:81], v[28:29], v[80:81], v[116:117]
	v_and_b32_sdwa v117, v78, v134 dst_sel:DWORD dst_unused:UNUSED_PAD src0_sel:WORD_1 src1_sel:DWORD
	v_pk_mul_f32 v[84:85], v[84:85], v[150:151] op_sel_hi:[1,0]
	v_pk_fma_f32 v[110:111], v[110:111], v[110:111], v[112:113]
	v_and_b32_e32 v87, 0xffff0000, v87
	v_add3_u32 v125, v88, v119, s19
	v_and_b32_e32 v89, 0xffff0000, v89
	v_and_b32_sdwa v116, v79, v134 dst_sel:DWORD dst_unused:UNUSED_PAD src0_sel:WORD_1 src1_sel:DWORD
	v_add3_u32 v135, v78, v117, s19
	v_and_b32_sdwa v117, v80, v134 dst_sel:DWORD dst_unused:UNUSED_PAD src0_sel:WORD_1 src1_sel:DWORD
	v_pk_fma_f32 v[84:85], v[36:37], v[84:85], v[114:115]
	v_and_b32_sdwa v114, v83, v134 dst_sel:DWORD dst_unused:UNUSED_PAD src0_sel:WORD_1 src1_sel:DWORD
	v_and_b32_sdwa v115, v82, v134 dst_sel:DWORD dst_unused:UNUSED_PAD src0_sel:WORD_1 src1_sel:DWORD
	v_pk_add_f32 v[108:109], v[108:109], v[110:111]
	v_and_b32_e32 v86, 0xffff0000, v124
	v_and_b32_e32 v88, 0xffff0000, v125
	v_add3_u32 v79, v79, v116, s19
	v_and_b32_e32 v78, 0xffff0000, v135
	v_and_b32_sdwa v116, v81, v134 dst_sel:DWORD dst_unused:UNUSED_PAD src0_sel:WORD_1 src1_sel:DWORD
	v_add3_u32 v136, v80, v117, s19
	v_add3_u32 v83, v83, v114, s19
	v_add3_u32 v137, v82, v115, s19
	v_and_b32_sdwa v114, v85, v134 dst_sel:DWORD dst_unused:UNUSED_PAD src0_sel:WORD_1 src1_sel:DWORD
	v_and_b32_sdwa v115, v84, v134 dst_sel:DWORD dst_unused:UNUSED_PAD src0_sel:WORD_1 src1_sel:DWORD
	v_pk_add_f32 v[108:109], v[108:109], v[108:109] op_sel_hi:[0,1]
	v_mov_b32_e32 v112, v87
	v_mov_b32_e32 v113, v89
	v_and_b32_e32 v79, 0xffff0000, v79
	v_add3_u32 v81, v81, v116, s19
	v_and_b32_e32 v80, 0xffff0000, v136
	v_add3_u32 v85, v85, v114, s19
	v_add3_u32 v138, v84, v115, s19
	v_mov_b32_e32 v110, v86
; #define GAS __attribute__((address_space(1)))
; __device__ __forceinline__ unsigned pk2(float lo, float hi) { return f2bf(lo) | (f2bf(hi) << 16); }
; __device__ __forceinline__ float bflo(unsigned w) { return __uint_as_float(w << 16); }
; __device__ __forceinline__ float bfhi(unsigned w) { return __uint_as_float(w & 0xffff0000u); }
; __device__ __forceinline__ float dot4(f32x4 a, f32x4 b) { return (a[0] * b[0] + a[1] * b[1]) + (a[2] * b[2] + a[3] * b[3]); }
;     ...
;                 else { v2u w; w.x = pk2(v[j][0], v[j][1]); w.y = pk2(v[j][2], v[j][3]); ((GAS v2u*)(Hout + (size_t)r * D))[lane + 64 * j] = w;
;                        v[j] = (f32x4){bflo(w.x), bfhi(w.x), bflo(w.y), bfhi(w.y)}; } }
;         }
;         if (MODE != 2) {
;             float ss = 0.f;
; #pragma unroll
;             for (int j = 0; j < 8; ++j) ss += dot4(v[j], v[j]);
;             ss = wave_sum(ss);
;             const float rs = 1.0f / sqrtf(ss * (1.0f / D) + EPS);
	v_mov_b32_e32 v111, v88
	v_pk_mul_f32 v[112:113], v[112:113], v[112:113]
	v_mul_f32_e32 v108, v78, v78
	v_and_b32_e32 v81, 0xffff0000, v81
	v_and_b32_e32 v83, 0xffff0000, v83
	v_and_b32_e32 v82, 0xffff0000, v137
	v_and_b32_e32 v85, 0xffff0000, v85
	v_and_b32_e32 v84, 0xffff0000, v138
	v_pk_fma_f32 v[110:111], v[110:111], v[110:111], v[112:113]
	v_pk_fma_f32 v[112:113], v[78:79], v[78:79], v[108:109] op_sel_hi:[1,1,0]
	v_mul_f32_e32 v108, v80, v80
	v_pk_add_f32 v[110:111], v[110:111], v[110:111] op_sel_hi:[0,1]
	v_pk_fma_f32 v[114:115], v[80:81], v[80:81], v[108:109] op_sel_hi:[1,1,0]
	v_pk_mul_f32 v[116:117], v[82:83], v[82:83]
	v_pk_mul_f32 v[118:119], v[84:85], v[84:85]
	v_mov_b32_e32 v112, v116
	v_mov_b32_e32 v114, v117
	v_mov_b32_e32 v110, v118
	v_mov_b32_e32 v108, v119
	v_pk_add_f32 v[112:113], v[112:113], v[114:115]
	v_pk_add_f32 v[108:109], v[110:111], v[108:109]
	v_and_b32_e32 v75, 0xffff0000, v75
	v_and_b32_e32 v77, 0xffff0000, v77
	v_pk_add_f32 v[108:109], v[112:113], v[108:109]
	v_and_b32_e32 v74, 0xffff0000, v139
	v_and_b32_e32 v76, 0xffff0000, v140
	v_and_b32_e32 v70, 0xffff0000, v141
	v_pk_add_f32 v[108:109], v[108:109], v[108:109] op_sel_hi:[0,1]
	v_mov_b32_e32 v112, v75
	v_mov_b32_e32 v113, v77
	v_and_b32_e32 v71, 0xffff0000, v71
	v_and_b32_e32 v72, 0xffff0000, v142
	v_mov_b32_e32 v110, v74
	v_mov_b32_e32 v111, v76
	v_pk_mul_f32 v[112:113], v[112:113], v[112:113]
	v_mul_f32_e32 v108, v70, v70
	v_and_b32_e32 v73, 0xffff0000, v73
	v_and_b32_e32 v67, 0xffff0000, v67
	v_and_b32_e32 v66, 0xffff0000, v143
	v_and_b32_e32 v69, 0xffff0000, v69
	v_and_b32_e32 v68, 0xffff0000, v144
	v_pk_fma_f32 v[110:111], v[110:111], v[110:111], v[112:113]
	v_pk_fma_f32 v[112:113], v[70:71], v[70:71], v[108:109] op_sel_hi:[1,1,0]
	v_mul_f32_e32 v108, v72, v72
	v_pk_add_f32 v[110:111], v[110:111], v[110:111] op_sel_hi:[0,1]
	v_pk_fma_f32 v[114:115], v[72:73], v[72:73], v[108:109] op_sel_hi:[1,1,0]
	v_pk_mul_f32 v[116:117], v[66:67], v[66:67]
	v_pk_mul_f32 v[118:119], v[68:69], v[68:69]
	v_mov_b32_e32 v112, v116
	v_mov_b32_e32 v114, v117
	v_mov_b32_e32 v110, v118
	v_mov_b32_e32 v108, v119
	v_pk_add_f32 v[112:113], v[112:113], v[114:115]
	v_pk_add_f32 v[108:109], v[110:111], v[108:109]
	v_or_b32_sdwa v110, v91, v122 dst_sel:DWORD dst_unused:UNUSED_PAD src0_sel:DWORD src1_sel:WORD_1
	v_pk_add_f32 v[108:109], v[112:113], v[108:109]
	v_or_b32_sdwa v111, v93, v123 dst_sel:DWORD dst_unused:UNUSED_PAD src0_sel:DWORD src1_sel:WORD_1
	v_add_f32_e32 v108, v108, v109
	ds_bpermute_b32 v109, v126, v108
	s_waitcnt lgkmcnt(0)
	v_add_f32_e32 v112, v108, v109
	ds_bpermute_b32 v113, v127, v112
	v_lshl_add_u64 v[108:109], v[98:99], 0, s[12:13]
	global_store_dwordx2 v[108:109], v[110:111], off
	v_or_b32_sdwa v110, v95, v120 dst_sel:DWORD dst_unused:UNUSED_PAD src0_sel:DWORD src1_sel:WORD_1
	v_or_b32_sdwa v111, v97, v121 dst_sel:DWORD dst_unused:UNUSED_PAD src0_sel:DWORD src1_sel:WORD_1
	s_waitcnt lgkmcnt(0)
	v_add_f32_e32 v112, v112, v113
	ds_bpermute_b32 v113, v128, v112
	global_store_dwordx2 v[108:109], v[110:111], off offset:512
	v_or_b32_sdwa v110, v87, v124 dst_sel:DWORD dst_unused:UNUSED_PAD src0_sel:DWORD src1_sel:WORD_1
	v_or_b32_sdwa v111, v89, v125 dst_sel:DWORD dst_unused:UNUSED_PAD src0_sel:DWORD src1_sel:WORD_1
	global_store_dwordx2 v[108:109], v[110:111], off offset:1024
	s_waitcnt lgkmcnt(0)
	v_add_f32_e32 v112, v112, v113
	ds_bpermute_b32 v113, v129, v112
	v_or_b32_sdwa v110, v79, v135 dst_sel:DWORD dst_unused:UNUSED_PAD src0_sel:DWORD src1_sel:WORD_1
	v_or_b32_sdwa v111, v81, v136 dst_sel:DWORD dst_unused:UNUSED_PAD src0_sel:DWORD src1_sel:WORD_1
	global_store_dwordx2 v[108:109], v[110:111], off offset:1536
	v_or_b32_sdwa v110, v83, v137 dst_sel:DWORD dst_unused:UNUSED_PAD src0_sel:DWORD src1_sel:WORD_1
	s_waitcnt lgkmcnt(0)
	v_add_f32_e32 v112, v112, v113
	ds_bpermute_b32 v113, v130, v112
	v_or_b32_sdwa v111, v85, v138 dst_sel:DWORD dst_unused:UNUSED_PAD src0_sel:DWORD src1_sel:WORD_1
	global_store_dwordx2 v[108:109], v[110:111], off offset:2048
	v_or_b32_sdwa v110, v75, v139 dst_sel:DWORD dst_unused:UNUSED_PAD src0_sel:DWORD src1_sel:WORD_1
	v_or_b32_sdwa v111, v77, v140 dst_sel:DWORD dst_unused:UNUSED_PAD src0_sel:DWORD src1_sel:WORD_1
	s_waitcnt lgkmcnt(0)
	v_add_f32_e32 v112, v112, v113
	ds_bpermute_b32 v113, v131, v112
	global_store_dwordx2 v[108:109], v[110:111], off offset:2560
	s_waitcnt lgkmcnt(0)
; #define GAS __attribute__((address_space(1)))
; __device__ __forceinline__ unsigned pk2(float lo, float hi) { return f2bf(lo) | (f2bf(hi) << 16); }
;     ...
;             const float rs = 1.0f / sqrtf(ss * (1.0f / D) + EPS);
;             float ga[8];
; #pragma unroll
;             for (int c = 0; c < 8; ++c) ga[c] = 0.f;
;             GAS v2u* op = (GAS v2u*)(XN + (size_t)r * D) + lane;
; #pragma unroll
;             for (int j = 0; j < 8; ++j) { const f32x4 g = gpr[j]; const f32x4 xn = (v[j] * rs) * g;
;                 v2u w; w.x = pk2(xn[0], xn[1]); w.y = pk2(xn[2], xn[3]); op[64 * j] = w;
	v_add_f32_e32 v110, v112, v113
	v_fmamk_f32 v110, v110, 0x3a000000, v132
	v_mul_f32_e32 v111, 0x4f800000, v110
	v_cmp_gt_f32_e32 vcc, s18, v110
	s_nop 1
	v_cndmask_b32_e32 v112, v110, v111, vcc
	v_sqrt_f32_e32 v113, v112
	v_or_b32_sdwa v110, v71, v141 dst_sel:DWORD dst_unused:UNUSED_PAD src0_sel:DWORD src1_sel:WORD_1
	v_or_b32_sdwa v111, v73, v142 dst_sel:DWORD dst_unused:UNUSED_PAD src0_sel:DWORD src1_sel:WORD_1
	global_store_dwordx2 v[108:109], v[110:111], off offset:3072
	v_add_u32_e32 v110, -1, v113
	v_fma_f32 v111, -v110, v113, v112
	v_cmp_ge_f32_e64 s[0:1], 0, v111
	v_add_u32_e32 v111, 1, v113
	s_nop 0
	v_cndmask_b32_e64 v110, v113, v110, s[0:1]
	v_fma_f32 v113, -v111, v113, v112
	v_cmp_lt_f32_e64 s[0:1], 0, v113
	s_nop 1
	v_cndmask_b32_e64 v110, v110, v111, s[0:1]
	v_mul_f32_e32 v111, 0x37800000, v110
	v_cndmask_b32_e32 v110, v110, v111, vcc
	v_cmp_class_f32_e32 vcc, v112, v133
	v_or_b32_sdwa v111, v69, v144 dst_sel:DWORD dst_unused:UNUSED_PAD src0_sel:DWORD src1_sel:WORD_1
	s_nop 0
	v_cndmask_b32_e32 v112, v110, v112, vcc
	v_div_scale_f32 v113, s[0:1], v112, v112, 1.0
	v_rcp_f32_e32 v114, v113
	v_or_b32_sdwa v110, v67, v143 dst_sel:DWORD dst_unused:UNUSED_PAD src0_sel:DWORD src1_sel:WORD_1
	global_store_dwordx2 v[108:109], v[110:111], off offset:3584
	v_fma_f32 v108, -v113, v114, 1.0
	v_fmac_f32_e32 v114, v108, v114
	v_div_scale_f32 v108, vcc, 1.0, v112, 1.0
	v_mul_f32_e32 v109, v108, v114
	v_fma_f32 v110, -v113, v109, v108
	v_fmac_f32_e32 v109, v110, v114
	v_fma_f32 v108, -v113, v109, v108
	v_div_fmas_f32 v108, v108, v114, v109
	v_div_fixup_f32 v108, v108, v112, 1.0
	v_pk_mul_f32 v[90:91], v[108:109], v[90:91] op_sel_hi:[0,1]
	v_pk_mul_f32 v[90:91], v[6:7], v[90:91]
	v_pk_mul_f32 v[92:93], v[108:109], v[92:93] op_sel_hi:[0,1]
	v_bfe_u32 v109, v90, 16, 1
	v_add3_u32 v90, v90, v109, s19
	v_bfe_u32 v109, v91, 16, 1
	v_pk_mul_f32 v[92:93], v[8:9], v[92:93]
	v_lshrrev_b32_e32 v90, 16, v90
	v_add3_u32 v91, v91, v109, s19
	v_and_or_b32 v90, v91, s16, v90
	v_bfe_u32 v91, v92, 16, 1
	v_add3_u32 v91, v92, v91, s19
	v_bfe_u32 v92, v93, 16, 1
	v_lshrrev_b32_e32 v91, 16, v91
	v_add3_u32 v92, v93, v92, s19
	v_lshl_add_u64 v[110:111], v[106:107], 0, s[12:13]
	v_and_or_b32 v91, v92, s16, v91
	global_store_dwordx2 v[110:111], v[90:91], off
	v_pk_mul_f32 v[90:91], v[108:109], v[94:95] op_sel_hi:[0,1]
	v_pk_mul_f32 v[90:91], v[14:15], v[90:91]
	v_pk_mul_f32 v[92:93], v[108:109], v[96:97] op_sel_hi:[0,1]
	v_bfe_u32 v94, v90, 16, 1
	v_add3_u32 v90, v90, v94, s19
	v_bfe_u32 v94, v91, 16, 1
	v_pk_mul_f32 v[92:93], v[16:17], v[92:93]
	v_lshrrev_b32_e32 v90, 16, v90
	v_add3_u32 v91, v91, v94, s19
	v_and_or_b32 v90, v91, s16, v90
	v_bfe_u32 v91, v92, 16, 1
	v_add3_u32 v91, v92, v91, s19
	v_bfe_u32 v92, v93, 16, 1
	v_lshrrev_b32_e32 v91, 16, v91
	v_add3_u32 v92, v93, v92, s19
	v_pk_mul_f32 v[86:87], v[108:109], v[86:87] op_sel_hi:[0,1]
	v_and_or_b32 v91, v92, s16, v91
	v_pk_mul_f32 v[86:87], v[22:23], v[86:87]
	global_store_dwordx2 v[110:111], v[90:91], off offset:512
	v_bfe_u32 v90, v86, 16, 1
	v_pk_mul_f32 v[88:89], v[108:109], v[88:89] op_sel_hi:[0,1]
	v_add3_u32 v86, v86, v90, s19
	v_bfe_u32 v90, v87, 16, 1
	v_pk_mul_f32 v[88:89], v[24:25], v[88:89]
	v_lshrrev_b32_e32 v86, 16, v86
	v_add3_u32 v87, v87, v90, s19
	v_and_or_b32 v86, v87, s16, v86
	v_bfe_u32 v87, v88, 16, 1
	v_add3_u32 v87, v88, v87, s19
	v_bfe_u32 v88, v89, 16, 1
	v_lshrrev_b32_e32 v87, 16, v87
	v_add3_u32 v88, v89, v88, s19
	v_pk_mul_f32 v[78:79], v[108:109], v[78:79] op_sel_hi:[0,1]
	v_and_or_b32 v87, v88, s16, v87
	v_pk_mul_f32 v[78:79], v[30:31], v[78:79]
	global_store_dwordx2 v[110:111], v[86:87], off offset:1024
	v_bfe_u32 v86, v78, 16, 1
	v_pk_mul_f32 v[80:81], v[108:109], v[80:81] op_sel_hi:[0,1]
	v_add3_u32 v78, v78, v86, s19
	v_bfe_u32 v86, v79, 16, 1
	v_pk_mul_f32 v[80:81], v[32:33], v[80:81]
	v_lshrrev_b32_e32 v78, 16, v78
	v_add3_u32 v79, v79, v86, s19
	v_and_or_b32 v78, v79, s16, v78
	v_bfe_u32 v79, v80, 16, 1
	v_add3_u32 v79, v80, v79, s19
	v_bfe_u32 v80, v81, 16, 1
	v_lshrrev_b32_e32 v79, 16, v79
	v_add3_u32 v80, v81, v80, s19
	v_and_or_b32 v79, v80, s16, v79
	global_store_dwordx2 v[110:111], v[78:79], off offset:1536
	v_pk_mul_f32 v[78:79], v[108:109], v[82:83] op_sel_hi:[0,1]
	v_pk_mul_f32 v[78:79], v[38:39], v[78:79]
	v_pk_mul_f32 v[80:81], v[108:109], v[84:85] op_sel_hi:[0,1]
	v_bfe_u32 v82, v78, 16, 1
	v_add3_u32 v78, v78, v82, s19
	v_bfe_u32 v82, v79, 16, 1
	v_pk_mul_f32 v[80:81], v[40:41], v[80:81]
	v_lshrrev_b32_e32 v78, 16, v78
	v_add3_u32 v79, v79, v82, s19
	v_and_or_b32 v78, v79, s16, v78
	v_bfe_u32 v79, v80, 16, 1
	v_add3_u32 v79, v80, v79, s19
	v_bfe_u32 v80, v81, 16, 1
	v_lshrrev_b32_e32 v79, 16, v79
	v_add3_u32 v80, v81, v80, s19
	v_pk_mul_f32 v[74:75], v[108:109], v[74:75] op_sel_hi:[0,1]
	v_and_or_b32 v79, v80, s16, v79
	v_pk_mul_f32 v[74:75], v[46:47], v[74:75]
	global_store_dwordx2 v[110:111], v[78:79], off offset:2048
	v_bfe_u32 v78, v74, 16, 1
	v_pk_mul_f32 v[76:77], v[108:109], v[76:77] op_sel_hi:[0,1]
	v_add3_u32 v74, v74, v78, s19
	v_bfe_u32 v78, v75, 16, 1
	v_pk_mul_f32 v[76:77], v[48:49], v[76:77]
	v_lshrrev_b32_e32 v74, 16, v74
	v_add3_u32 v75, v75, v78, s19
	v_and_or_b32 v74, v75, s16, v74
	v_bfe_u32 v75, v76, 16, 1
	v_add3_u32 v75, v76, v75, s19
	v_bfe_u32 v76, v77, 16, 1
	v_lshrrev_b32_e32 v75, 16, v75
	v_add3_u32 v76, v77, v76, s19
	v_pk_mul_f32 v[70:71], v[108:109], v[70:71] op_sel_hi:[0,1]
	v_and_or_b32 v75, v76, s16, v75
	v_pk_mul_f32 v[70:71], v[54:55], v[70:71]
	global_store_dwordx2 v[110:111], v[74:75], off offset:2560
	v_bfe_u32 v74, v70, 16, 1
	v_pk_mul_f32 v[72:73], v[108:109], v[72:73] op_sel_hi:[0,1]
	v_add3_u32 v70, v70, v74, s19
	v_bfe_u32 v74, v71, 16, 1
	v_pk_mul_f32 v[72:73], v[56:57], v[72:73]
	v_lshrrev_b32_e32 v70, 16, v70
	v_add3_u32 v71, v71, v74, s19
	v_and_or_b32 v70, v71, s16, v70
	v_bfe_u32 v71, v72, 16, 1
	v_add3_u32 v71, v72, v71, s19
	v_bfe_u32 v72, v73, 16, 1
	v_lshrrev_b32_e32 v71, 16, v71
	v_add3_u32 v72, v73, v72, s19
	v_pk_mul_f32 v[66:67], v[108:109], v[66:67] op_sel_hi:[0,1]
	v_and_or_b32 v71, v72, s16, v71
	v_pk_mul_f32 v[66:67], v[62:63], v[66:67]
	global_store_dwordx2 v[110:111], v[70:71], off offset:3072
	v_bfe_u32 v70, v66, 16, 1
	v_pk_mul_f32 v[68:69], v[108:109], v[68:69] op_sel_hi:[0,1]
	v_add3_u32 v66, v66, v70, s19
	v_bfe_u32 v70, v67, 16, 1
	v_pk_mul_f32 v[68:69], v[64:65], v[68:69]
	v_lshrrev_b32_e32 v66, 16, v66
	v_add3_u32 v67, v67, v70, s19
	v_and_or_b32 v66, v67, s16, v66
	v_bfe_u32 v67, v68, 16, 1
	v_add3_u32 v67, v68, v67, s19
	v_bfe_u32 v68, v69, 16, 1
	v_lshrrev_b32_e32 v67, 16, v67
	v_add3_u32 v68, v69, v68, s19
	v_and_or_b32 v67, v68, s16, v67
	global_store_dwordx2 v[110:111], v[66:67], off offset:3584
	s_cbranch_scc0 .LBB0_1493
; #define GAS __attribute__((address_space(1)))
; __device__ __forceinline__ float bflo(unsigned w) { return __uint_as_float(w << 16); }
; __device__ __forceinline__ float bfhi(unsigned w) { return __uint_as_float(w & 0xffff0000u); }
; __device__ __forceinline__ float sigmf(float x) { return __builtin_amdgcn_rcpf(1.0f + __expf(-x)); }
; __device__ __forceinline__ float dot4(f32x4 a, f32x4 b) { return (a[0] * b[0] + a[1] * b[1]) + (a[2] * b[2] + a[3] * b[3]); }
;     ...
;     for (int r = gw; r < M; r += NGW) {
;         f32x4 v[8];
;         if (RES) { const GAS v2u* rp = (const GAS v2u*)(RES + (size_t)r * D) + lane;
; #pragma unroll
;             for (int j = 0; j < 8; ++j) { const v2u w = rp[64 * j]; v[j] = (f32x4){bflo(w.x), bfhi(w.x), bflo(w.y), bfhi(w.y)}; } }
;         else { const GAS f32x4* rp = (const GAS f32x4*)xrow(a, r) + lane;
; #pragma unroll
;             for (int j = 0; j < 8; ++j) v[j] = rp[64 * j]; }
;         if (MODE != 0) {
;             const GAS v2u* tp = (const GAS v2u*)(T + (size_t)r * D) + lane;
;             f32x4 t[8]; float ss = 0.f;
;             if (TSRC != 0 && r >= NP) {
;                 const GAS f32x4* sp = (const GAS f32x4*)(WSP(float, WS_SLAB) + (size_t)(r - NP) * D) + lane;
; #pragma unroll
;                 for (int j = 0; j < 8; ++j) t[j] = sp[64 * j];
;                 _Pragma("unroll 1") for (int s = 1; s < nslab; ++s) { sp += (size_t)NS * D / 4;
; #pragma unroll
;                     for (int j = 0; j < 8; ++j) t[j] += sp[64 * j]; }
;                 if (TSRC == 2) { const GAS v2u* pp = (const GAS v2u*)(PUP + (size_t)r * D) + lane;
; #pragma unroll
;                     for (int j = 0; j < 8; ++j) { const v2u pw = pp[64 * j]; const f32x4 p = (f32x4){bflo(pw.x), bfhi(pw.x), bflo(pw.y), bfhi(pw.y)}; t[j] = (f32x4){sigmf(t[j][0]), sigmf(t[j][1]), sigmf(t[j][2]), sigmf(t[j][3])} * p; } }
; #pragma unroll
;                 for (int j = 0; j < 8; ++j) ss += dot4(t[j], t[j]);
;             } else {
; #pragma unroll
;                 for (int j = 0; j < 8; ++j) { const v2u tw = tp[64 * j]; t[j] = (f32x4){bflo(tw.x), bfhi(tw.x), bflo(tw.y), bfhi(tw.y)}; ss += dot4(t[j], t[j]); }
.LBB0_1487:
	s_cmp_lt_i32 s8, s3
	s_cbranch_scc1 .Lrowpf1487_orig
	s_cmpk_gt_i32 s8, 0x1fff
	s_cbranch_scc1 .Lrowpf1487_orig
	s_waitcnt vmcnt(16)
	s_ashr_i32 s9, s8, 31
	s_lshl_b64 s[0:1], s[8:9], 12
	v_lshl_add_u64 v[66:67], v[98:99], 0, s[0:1]
	v_mov_b32_e32 v122, v168
	v_mov_b32_e32 v123, v169
	v_mov_b32_e32 v120, v170
	v_mov_b32_e32 v121, v171
	v_mov_b32_e32 v118, v172
	v_mov_b32_e32 v119, v173
	v_mov_b32_e32 v116, v174
	v_mov_b32_e32 v117, v175
	v_mov_b32_e32 v114, v176
	v_mov_b32_e32 v115, v177
	v_mov_b32_e32 v112, v178
	v_mov_b32_e32 v113, v179
	v_mov_b32_e32 v110, v180
	v_mov_b32_e32 v111, v181
	v_mov_b32_e32 v108, v182
	v_mov_b32_e32 v109, v183
	s_lshl_b64 s[12:13], s[8:9], 11
	s_cmpk_gt_i32 s8, 0x1fff
	s_mov_b64 s[0:1], -1
	v_lshl_add_u64 v[66:67], s[12:13], 1, v[100:101]
	v_mov_b32_e32 v68, v184
	v_mov_b32_e32 v69, v185
	v_mov_b32_e32 v70, v186
	v_mov_b32_e32 v71, v187
	v_mov_b32_e32 v72, v188
	v_mov_b32_e32 v73, v189
	v_mov_b32_e32 v74, v190
	v_mov_b32_e32 v75, v191
	v_mov_b32_e32 v76, v192
	v_mov_b32_e32 v77, v193
	v_mov_b32_e32 v82, v194
	v_mov_b32_e32 v83, v195
	v_mov_b32_e32 v84, v196
	v_mov_b32_e32 v85, v197
	v_mov_b32_e32 v94, v198
	v_mov_b32_e32 v95, v199
	s_mov_b64 s[0:1], 0
	s_branch .Lrowpf1487_conv

; #define GAS __attribute__((address_space(1)))
; __device__ __forceinline__ float bflo(unsigned w) { return __uint_as_float(w << 16); }
; __device__ __forceinline__ float bfhi(unsigned w) { return __uint_as_float(w & 0xffff0000u); }
; __device__ __forceinline__ float sigmf(float x) { return __builtin_amdgcn_rcpf(1.0f + __expf(-x)); }
; __device__ __forceinline__ float dot4(f32x4 a, f32x4 b) { return (a[0] * b[0] + a[1] * b[1]) + (a[2] * b[2] + a[3] * b[3]); }
;     ...
;         if (RES) { const GAS v2u* rp = (const GAS v2u*)(RES + (size_t)r * D) + lane;
; #pragma unroll
;             for (int j = 0; j < 8; ++j) { const v2u w = rp[64 * j]; v[j] = (f32x4){bflo(w.x), bfhi(w.x), bflo(w.y), bfhi(w.y)}; } }
;         else { const GAS f32x4* rp = (const GAS f32x4*)xrow(a, r) + lane;
; #pragma unroll
;             for (int j = 0; j < 8; ++j) v[j] = rp[64 * j]; }
;         if (MODE != 0) {
;             const GAS v2u* tp = (const GAS v2u*)(T + (size_t)r * D) + lane;
;             f32x4 t[8]; float ss = 0.f;
;             if (TSRC != 0 && r >= NP) {
;                 const GAS f32x4* sp = (const GAS f32x4*)(WSP(float, WS_SLAB) + (size_t)(r - NP) * D) + lane;
; #pragma unroll
;                 for (int j = 0; j < 8; ++j) t[j] = sp[64 * j];
;                 _Pragma("unroll 1") for (int s = 1; s < nslab; ++s) { sp += (size_t)NS * D / 4;
; #pragma unroll
;                     for (int j = 0; j < 8; ++j) t[j] += sp[64 * j]; }
;                 if (TSRC == 2) { const GAS v2u* pp = (const GAS v2u*)(PUP + (size_t)r * D) + lane;
; #pragma unroll
;                     for (int j = 0; j < 8; ++j) { const v2u pw = pp[64 * j]; const f32x4 p = (f32x4){bflo(pw.x), bfhi(pw.x), bflo(pw.y), bfhi(pw.y)}; t[j] = (f32x4){sigmf(t[j][0]), sigmf(t[j][1]), sigmf(t[j][2]), sigmf(t[j][3])} * p; } }
; #pragma unroll
;                 for (int j = 0; j < 8; ++j) ss += dot4(t[j], t[j]);
;             } else {
; #pragma unroll
;                 for (int j = 0; j < 8; ++j) { const v2u tw = tp[64 * j]; t[j] = (f32x4){bflo(tw.x), bfhi(tw.x), bflo(tw.y), bfhi(tw.y)}; ss += dot4(t[j], t[j]); }
.Lrowpf1487_conv:
	v_and_b32_e32 v91, 0xffff0000, v68
	v_and_b32_e32 v93, 0xffff0000, v69
	v_and_b32_e32 v137, 0xffff0000, v71
	v_and_b32_e32 v136, 0xffff0000, v70
	v_lshlrev_b32_e32 v78, 16, v74
	v_lshlrev_b32_e32 v90, 16, v68
	v_lshlrev_b32_e32 v92, 16, v69
	v_lshlrev_b32_e32 v125, 16, v71
	v_lshlrev_b32_e32 v124, 16, v70
	v_lshlrev_b32_e32 v68, 16, v95
	v_and_b32_e32 v69, 0xffff0000, v95
	v_mul_f32_e32 v144, v93, v93
	v_mov_b32_e32 v95, v136
	v_mov_b32_e32 v97, v137
	v_pk_mul_f32 v[136:137], v[136:137], v[136:137]
	v_mul_f32_e32 v146, v91, v91
	v_mov_b32_e32 v145, v78
	v_mov_b32_e32 v147, v78
	v_and_b32_e32 v87, 0xffff0000, v72
	v_and_b32_e32 v89, 0xffff0000, v73
	v_and_b32_e32 v79, 0xffff0000, v74
	v_lshlrev_b32_e32 v80, 16, v75
	v_and_b32_e32 v81, 0xffff0000, v75
	v_and_b32_e32 v75, 0xffff0000, v77
	v_and_b32_e32 v74, 0xffff0000, v76
	v_and_b32_e32 v143, 0xffff0000, v83
	v_and_b32_e32 v142, 0xffff0000, v82
	v_lshlrev_b32_e32 v66, 16, v94
	v_and_b32_e32 v67, 0xffff0000, v94
	v_mov_b32_e32 v94, v124
	v_mov_b32_e32 v96, v125
	v_pk_fma_f32 v[154:155], v[92:93], v[92:93], v[144:145] op_sel_hi:[1,1,0]
	v_pk_fma_f32 v[124:125], v[124:125], v[124:125], v[136:137]
	v_pk_fma_f32 v[136:137], v[90:91], v[90:91], v[146:147] op_sel_hi:[1,1,0]
	v_lshlrev_b32_e32 v86, 16, v72
	v_lshlrev_b32_e32 v88, 16, v73
	v_lshlrev_b32_e32 v139, 16, v77
	v_lshlrev_b32_e32 v141, 16, v83
	v_lshlrev_b32_e32 v140, 16, v82
	v_lshlrev_b32_e32 v72, 16, v85
	v_and_b32_e32 v73, 0xffff0000, v85
	v_mul_f32_e32 v148, v87, v87
	v_mul_f32_e32 v150, v89, v89
	v_mov_b32_e32 v85, v75
	v_pk_mul_f32 v[152:153], v[74:75], v[74:75]
	v_mov_b32_e32 v75, v142
	v_mov_b32_e32 v77, v143
	v_pk_mul_f32 v[142:143], v[142:143], v[142:143]
	v_mov_b32_e32 v149, v66
	v_mov_b32_e32 v144, v136
	v_mov_b32_e32 v146, v154
	v_lshlrev_b32_e32 v138, 16, v76
	v_mul_f32_e32 v135, v79, v79
	v_mul_f32_e32 v158, v80, v80
	v_mul_f32_e32 v159, v81, v81
	v_mov_b32_e32 v83, v74
	v_mov_b32_e32 v74, v140
	v_mov_b32_e32 v76, v141
	v_pk_fma_f32 v[156:157], v[86:87], v[86:87], v[148:149] op_sel_hi:[1,1,0]
	v_pk_fma_f32 v[150:151], v[88:89], v[88:89], v[150:151] op_sel_hi:[1,1,0]
	v_pk_fma_f32 v[140:141], v[140:141], v[140:141], v[142:143]
	v_pk_add_f32 v[136:137], v[136:137], v[154:155]
	v_pk_add_f32 v[124:125], v[124:125], v[124:125] op_sel:[0,1] op_sel_hi:[1,0]
	v_pk_mul_f32 v[142:143], v[144:145], v[146:147]
	v_mov_b32_e32 v157, v158
	v_mov_b32_e32 v151, v159
	v_mov_b32_e32 v125, v135
	v_mov_b32_e32 v137, v143
	v_pk_add_f32 v[144:145], v[156:157], v[150:151]
	v_pk_add_f32 v[124:125], v[136:137], v[124:125]
	v_lshlrev_b32_e32 v70, 16, v84
	v_and_b32_e32 v71, 0xffff0000, v84
	v_mov_b32_e32 v82, v138
	v_mov_b32_e32 v84, v139
	v_pk_fma_f32 v[138:139], v[138:139], v[138:139], v[152:153]
	v_pk_add_f32 v[124:125], v[124:125], v[144:145]
	v_pk_add_f32 v[138:139], v[138:139], v[138:139] op_sel:[0,1] op_sel_hi:[1,0]
	v_pk_add_f32 v[124:125], v[124:125], v[124:125] op_sel:[0,1] op_sel_hi:[1,0]
	v_mov_b32_e32 v136, v138
	v_mov_b32_e32 v148, v124
	v_mov_b32_e32 v137, v66
	v_pk_add_f32 v[124:125], v[124:125], v[138:139]
	v_pk_mul_f32 v[136:137], v[148:149], v[136:137]
	v_mul_f32_e32 v160, v67, v67
	v_mov_b32_e32 v125, v137
	v_pk_add_f32 v[136:137], v[140:141], v[140:141] op_sel:[0,1] op_sel_hi:[1,0]
	v_mul_f32_e32 v138, v73, v73
	v_mov_b32_e32 v137, v160
	v_pk_add_f32 v[124:125], v[124:125], v[136:137]
	v_mul_f32_e32 v136, v71, v71
	v_mul_f32_e32 v161, v68, v68
	v_mul_f32_e32 v162, v69, v69
	v_pk_fma_f32 v[136:137], v[70:71], v[70:71], v[136:137] op_sel_hi:[1,1,0]
	v_pk_fma_f32 v[138:139], v[72:73], v[72:73], v[138:139] op_sel_hi:[1,1,0]
	v_mov_b32_e32 v137, v161
	v_mov_b32_e32 v139, v162
	v_pk_add_f32 v[136:137], v[136:137], v[138:139]
	s_nop 0
	v_pk_add_f32 v[124:125], v[124:125], v[136:137]
	s_nop 0
	v_add_f32_e32 v124, v124, v125

; #define GAS __attribute__((address_space(1)))
; __device__ __forceinline__ unsigned pk2(float lo, float hi) { return f2bf(lo) | (f2bf(hi) << 16); }
;     ...
;     for (int r = gw; r < M; r += NGW) {
;         f32x4 v[8];
;         if (RES) { const GAS v2u* rp = (const GAS v2u*)(RES + (size_t)r * D) + lane;
; #pragma unroll
;             for (int j = 0; j < 8; ++j) { const v2u w = rp[64 * j]; v[j] = (f32x4){bflo(w.x), bfhi(w.x), bflo(w.y), bfhi(w.y)}; } }
;         else { const GAS f32x4* rp = (const GAS f32x4*)xrow(a, r) + lane;
; #pragma unroll
;             for (int j = 0; j < 8; ++j) v[j] = rp[64 * j]; }
;         if (MODE != 0) {
;             const GAS v2u* tp = (const GAS v2u*)(T + (size_t)r * D) + lane;
;             f32x4 t[8]; float ss = 0.f;
;             if (TSRC != 0 && r >= NP) {
;                 const GAS f32x4* sp = (const GAS f32x4*)(WSP(float, WS_SLAB) + (size_t)(r - NP) * D) + lane;
; #pragma unroll
;                 for (int j = 0; j < 8; ++j) t[j] = sp[64 * j];
;                 _Pragma("unroll 1") for (int s = 1; s < nslab; ++s) { sp += (size_t)NS * D / 4;
; #pragma unroll
;                     for (int j = 0; j < 8; ++j) t[j] += sp[64 * j]; }
;                 if (TSRC == 2) { const GAS v2u* pp = (const GAS v2u*)(PUP + (size_t)r * D) + lane;
; #pragma unroll
;                     for (int j = 0; j < 8; ++j) { const v2u pw = pp[64 * j]; const f32x4 p = (f32x4){bflo(pw.x), bfhi(pw.x), bflo(pw.y), bfhi(pw.y)}; t[j] = (f32x4){sigmf(t[j][0]), sigmf(t[j][1]), sigmf(t[j][2]), sigmf(t[j][3])} * p; } }
; #pragma unroll
;                 for (int j = 0; j < 8; ++j) ss += dot4(t[j], t[j]);
;             } else {
; #pragma unroll
;                 for (int j = 0; j < 8; ++j) { const v2u tw = tp[64 * j]; t[j] = (f32x4){bflo(tw.x), bfhi(tw.x), bflo(tw.y), bfhi(tw.y)}; ss += dot4(t[j], t[j]); }
;             }
;             ss = wave_sum(ss);
;             const float rs = sc * (1.0f / sqrtf(ss * (1.0f / D) + EPS));
; #pragma unroll
;             for (int j = 0; j < 8; ++j) { const f32x4 g = gpo[j]; v[j] = v[j] + (t[j] * rs) * g;
;                 if (MODE == 2) ((GAS f32x4*)(Yout + (size_t)r * D))[lane + 64 * j] = v[j];
;                 else { v2u w; w.x = pk2(v[j][0], v[j][1]); w.y = pk2(v[j][2], v[j][3]); ((GAS v2u*)(Hout + (size_t)r * D))[lane + 64 * j] = w;
;                        v[j] = (f32x4){bflo(w.x), bfhi(w.x), bflo(w.y), bfhi(w.y)}; } }
.LBB0_1751:
	ds_bpermute_b32 v125, v126, v124
	s_add_i32 s60, s6, s3
	s_cmpk_gt_i32 s60, 0x1fff
	s_cbranch_scc1 .Lrowpf1752_skip
	s_lshl_b32 s60, s60, 12
	s_mov_b32 s61, 0
	v_lshl_add_u64 v[200:201], v[98:99], 0, s[60:61]
	global_load_dwordx2 v[168:169], v[200:201], off
	global_load_dwordx2 v[170:171], v[200:201], off offset:512
	global_load_dwordx2 v[172:173], v[200:201], off offset:1024
	global_load_dwordx2 v[174:175], v[200:201], off offset:1536
	global_load_dwordx2 v[176:177], v[200:201], off offset:2048
	global_load_dwordx2 v[178:179], v[200:201], off offset:2560
	global_load_dwordx2 v[180:181], v[200:201], off offset:3072
	global_load_dwordx2 v[182:183], v[200:201], off offset:3584
	s_nop 0
	v_lshl_add_u64 v[200:201], v[100:101], 0, s[60:61]
	global_load_dwordx2 v[184:185], v[200:201], off
	global_load_dwordx2 v[186:187], v[200:201], off offset:512
	global_load_dwordx2 v[188:189], v[200:201], off offset:1024
	global_load_dwordx2 v[190:191], v[200:201], off offset:1536
	global_load_dwordx2 v[192:193], v[200:201], off offset:2048
	global_load_dwordx2 v[194:195], v[200:201], off offset:2560
	global_load_dwordx2 v[196:197], v[200:201], off offset:3072
	global_load_dwordx2 v[198:199], v[200:201], off offset:3584
.Lrowpf1752_skip:
	v_and_b32_e32 v147, 0xffff0000, v110
	v_and_b32_e32 v149, 0xffff0000, v111
	v_lshlrev_b32_e32 v136, 16, v122
	v_and_b32_e32 v137, 0xffff0000, v122
	s_waitcnt lgkmcnt(0)
	v_add_f32_e32 v135, v124, v125
	ds_bpermute_b32 v140, v127, v135
	v_lshlrev_b32_e32 v138, 16, v120
	v_and_b32_e32 v139, 0xffff0000, v120
	v_and_b32_e32 v145, 0xffff0000, v112
	v_lshlrev_b32_e32 v122, 16, v123
	s_waitcnt lgkmcnt(0)
	v_add_f32_e32 v135, v135, v140
	ds_bpermute_b32 v142, v128, v135
	v_and_b32_e32 v123, 0xffff0000, v123
	v_lshlrev_b32_e32 v120, 16, v121
	v_and_b32_e32 v121, 0xffff0000, v121
	v_lshlrev_b32_e32 v140, 16, v116
	s_waitcnt lgkmcnt(0)
	v_add_f32_e32 v135, v135, v142
	ds_bpermute_b32 v144, v129, v135
	v_and_b32_e32 v141, 0xffff0000, v116
	v_lshlrev_b32_e32 v124, 16, v118
	v_and_b32_e32 v125, 0xffff0000, v118
	v_lshlrev_b32_e32 v142, 16, v114
	s_waitcnt lgkmcnt(0)
	v_add_f32_e32 v135, v135, v144
	ds_bpermute_b32 v146, v130, v135
	v_lshlrev_b32_e32 v144, 16, v112
	v_lshlrev_b32_e32 v112, 16, v113
	v_and_b32_e32 v113, 0xffff0000, v113
	v_and_b32_e32 v143, 0xffff0000, v114
	s_waitcnt lgkmcnt(0)
	v_add_f32_e32 v135, v135, v146
	ds_bpermute_b32 v148, v131, v135
	v_lshlrev_b32_e32 v146, 16, v110
	v_lshlrev_b32_e32 v118, 16, v119
	v_and_b32_e32 v119, 0xffff0000, v119
	v_lshlrev_b32_e32 v116, 16, v117
	s_waitcnt lgkmcnt(0)
	v_add_f32_e32 v110, v135, v148
	v_fmamk_f32 v110, v110, 0x3a000000, v132
	v_mul_f32_e32 v135, 0x4f800000, v110
	v_cmp_gt_f32_e32 vcc, s16, v110
	v_lshlrev_b32_e32 v148, 16, v111
	v_and_b32_e32 v117, 0xffff0000, v117
	v_cndmask_b32_e32 v135, v110, v135, vcc
	v_sqrt_f32_e32 v150, v135
	v_lshlrev_b32_e32 v110, 16, v108
	v_lshlrev_b32_e32 v114, 16, v115
	v_and_b32_e32 v115, 0xffff0000, v115
	v_add_u32_e32 v111, -1, v150
	v_fma_f32 v151, -v111, v150, v135
	v_cmp_ge_f32_e64 s[0:1], 0, v151
	v_add_u32_e32 v151, 1, v150
	s_lshl_b64 s[10:11], s[10:11], 1
	v_cndmask_b32_e64 v111, v150, v111, s[0:1]
	v_fma_f32 v150, -v151, v150, v135
	v_cmp_lt_f32_e64 s[0:1], 0, v150
	s_add_i32 s6, s6, s3
	s_add_i32 s8, s8, s3
	v_cndmask_b32_e64 v111, v111, v151, s[0:1]
	v_mul_f32_e32 v150, 0x37800000, v111
	v_cndmask_b32_e32 v111, v111, v150, vcc
	v_cmp_class_f32_e32 vcc, v135, v133
	s_cmpk_lt_i32 s6, 0x2200
	s_nop 0
	v_cndmask_b32_e32 v135, v111, v135, vcc
	v_div_scale_f32 v150, s[0:1], v135, v135, 1.0
	v_rcp_f32_e32 v151, v150
	v_and_b32_e32 v111, 0xffff0000, v108
	v_lshlrev_b32_e32 v108, 16, v109
	v_and_b32_e32 v109, 0xffff0000, v109
	v_fma_f32 v152, -v150, v151, 1.0
	v_fmac_f32_e32 v151, v152, v151
	v_div_scale_f32 v152, vcc, 1.0, v135, 1.0
	v_mul_f32_e32 v153, v152, v151
	v_fma_f32 v154, -v150, v153, v152
	v_fmac_f32_e32 v153, v154, v151
	v_fma_f32 v150, -v150, v153, v152
	v_div_fmas_f32 v150, v150, v151, v153
	v_div_fixup_f32 v135, v150, v135, 1.0
	v_mul_f32_e32 v150, 0.5, v135
	v_pk_mul_f32 v[90:91], v[90:91], v[150:151] op_sel_hi:[1,0]
	v_pk_mul_f32 v[94:95], v[94:95], v[150:151] op_sel_hi:[1,0]
	v_pk_mul_f32 v[74:75], v[74:75], v[150:151] op_sel_hi:[1,0]
	v_pk_mul_f32 v[92:93], v[92:93], v[150:151] op_sel_hi:[1,0]
	v_pk_fma_f32 v[90:91], v[2:3], v[90:91], v[136:137]
	v_pk_mul_f32 v[96:97], v[96:97], v[150:151] op_sel_hi:[1,0]
	v_pk_fma_f32 v[94:95], v[10:11], v[94:95], v[138:139]
	v_pk_mul_f32 v[76:77], v[76:77], v[150:151] op_sel_hi:[1,0]
	v_pk_fma_f32 v[74:75], v[42:43], v[74:75], v[144:145]
	v_pk_fma_f32 v[92:93], v[4:5], v[92:93], v[122:123]
	v_and_b32_sdwa v122, v91, v134 dst_sel:DWORD dst_unused:UNUSED_PAD src0_sel:WORD_1 src1_sel:DWORD
	v_and_b32_sdwa v123, v90, v134 dst_sel:DWORD dst_unused:UNUSED_PAD src0_sel:WORD_1 src1_sel:DWORD
	v_pk_fma_f32 v[96:97], v[12:13], v[96:97], v[120:121]
	v_and_b32_sdwa v120, v95, v134 dst_sel:DWORD dst_unused:UNUSED_PAD src0_sel:WORD_1 src1_sel:DWORD
	v_and_b32_sdwa v121, v94, v134 dst_sel:DWORD dst_unused:UNUSED_PAD src0_sel:WORD_1 src1_sel:DWORD
	v_pk_fma_f32 v[76:77], v[44:45], v[76:77], v[112:113]
	v_and_b32_sdwa v112, v75, v134 dst_sel:DWORD dst_unused:UNUSED_PAD src0_sel:WORD_1 src1_sel:DWORD
	v_and_b32_sdwa v113, v74, v134 dst_sel:DWORD dst_unused:UNUSED_PAD src0_sel:WORD_1 src1_sel:DWORD
	v_pk_mul_f32 v[70:71], v[70:71], v[150:151] op_sel_hi:[1,0]
	v_pk_mul_f32 v[66:67], v[66:67], v[150:151] op_sel_hi:[1,0]
	v_add3_u32 v91, v91, v122, s17
	v_add3_u32 v122, v90, v123, s17
	v_and_b32_sdwa v123, v93, v134 dst_sel:DWORD dst_unused:UNUSED_PAD src0_sel:WORD_1 src1_sel:DWORD
; #define GAS __attribute__((address_space(1)))
; __device__ __forceinline__ unsigned pk2(float lo, float hi) { return f2bf(lo) | (f2bf(hi) << 16); }
; __device__ __forceinline__ float bflo(unsigned w) { return __uint_as_float(w << 16); }
; __device__ __forceinline__ float bfhi(unsigned w) { return __uint_as_float(w & 0xffff0000u); }
; __device__ __forceinline__ float dot4(f32x4 a, f32x4 b) { return (a[0] * b[0] + a[1] * b[1]) + (a[2] * b[2] + a[3] * b[3]); }
;     ...
;             for (int j = 0; j < 8; ++j) { const f32x4 g = gpo[j]; v[j] = v[j] + (t[j] * rs) * g;
;                 if (MODE == 2) ((GAS f32x4*)(Yout + (size_t)r * D))[lane + 64 * j] = v[j];
;                 else { v2u w; w.x = pk2(v[j][0], v[j][1]); w.y = pk2(v[j][2], v[j][3]); ((GAS v2u*)(Hout + (size_t)r * D))[lane + 64 * j] = w;
;                        v[j] = (f32x4){bflo(w.x), bfhi(w.x), bflo(w.y), bfhi(w.y)}; } }
;         }
;         if (MODE != 2) {
;             float ss = 0.f;
; #pragma unroll
;             for (int j = 0; j < 8; ++j) ss += dot4(v[j], v[j]);
;             ss = wave_sum(ss);
	v_and_b32_sdwa v135, v92, v134 dst_sel:DWORD dst_unused:UNUSED_PAD src0_sel:WORD_1 src1_sel:DWORD
	v_add3_u32 v95, v95, v120, s17
	v_add3_u32 v120, v94, v121, s17
	v_and_b32_sdwa v121, v97, v134 dst_sel:DWORD dst_unused:UNUSED_PAD src0_sel:WORD_1 src1_sel:DWORD
	v_pk_mul_f32 v[78:79], v[78:79], v[150:151] op_sel_hi:[1,0]
	v_add3_u32 v75, v75, v112, s17
	v_add3_u32 v139, v74, v113, s17
	v_and_b32_sdwa v112, v77, v134 dst_sel:DWORD dst_unused:UNUSED_PAD src0_sel:WORD_1 src1_sel:DWORD
	v_and_b32_sdwa v113, v76, v134 dst_sel:DWORD dst_unused:UNUSED_PAD src0_sel:WORD_1 src1_sel:DWORD
	v_pk_mul_f32 v[72:73], v[72:73], v[150:151] op_sel_hi:[1,0]
	v_pk_fma_f32 v[70:71], v[50:51], v[70:71], v[146:147]
	v_pk_mul_f32 v[68:69], v[68:69], v[150:151] op_sel_hi:[1,0]
	v_pk_fma_f32 v[66:67], v[58:59], v[66:67], v[110:111]
	v_and_b32_e32 v91, 0xffff0000, v91
	v_add3_u32 v93, v93, v123, s17
	v_add3_u32 v123, v92, v135, s17
	v_and_b32_e32 v95, 0xffff0000, v95
	v_and_b32_sdwa v135, v96, v134 dst_sel:DWORD dst_unused:UNUSED_PAD src0_sel:WORD_1 src1_sel:DWORD
	v_add3_u32 v97, v97, v121, s17
	v_pk_mul_f32 v[86:87], v[86:87], v[150:151] op_sel_hi:[1,0]
	v_pk_fma_f32 v[78:79], v[26:27], v[78:79], v[140:141]
	v_pk_mul_f32 v[82:83], v[82:83], v[150:151] op_sel_hi:[1,0]
	v_add3_u32 v77, v77, v112, s17
	v_add3_u32 v140, v76, v113, s17
	v_pk_fma_f32 v[72:73], v[52:53], v[72:73], v[148:149]
	v_and_b32_sdwa v112, v71, v134 dst_sel:DWORD dst_unused:UNUSED_PAD src0_sel:WORD_1 src1_sel:DWORD
	v_and_b32_sdwa v113, v70, v134 dst_sel:DWORD dst_unused:UNUSED_PAD src0_sel:WORD_1 src1_sel:DWORD
	v_pk_fma_f32 v[68:69], v[60:61], v[68:69], v[108:109]
	v_and_b32_sdwa v108, v67, v134 dst_sel:DWORD dst_unused:UNUSED_PAD src0_sel:WORD_1 src1_sel:DWORD
	v_and_b32_sdwa v109, v66, v134 dst_sel:DWORD dst_unused:UNUSED_PAD src0_sel:WORD_1 src1_sel:DWORD
	v_and_b32_e32 v90, 0xffff0000, v122
	v_and_b32_e32 v93, 0xffff0000, v93
	v_and_b32_e32 v94, 0xffff0000, v120
	v_add3_u32 v121, v96, v135, s17
	v_and_b32_e32 v97, 0xffff0000, v97
	v_pk_mul_f32 v[88:89], v[88:89], v[150:151] op_sel_hi:[1,0]
	v_pk_fma_f32 v[86:87], v[18:19], v[86:87], v[124:125]
	v_pk_fma_f32 v[82:83], v[34:35], v[82:83], v[142:143]
	v_add3_u32 v71, v71, v112, s17
	v_add3_u32 v141, v70, v113, s17
	v_and_b32_sdwa v112, v73, v134 dst_sel:DWORD dst_unused:UNUSED_PAD src0_sel:WORD_1 src1_sel:DWORD
	v_and_b32_sdwa v113, v72, v134 dst_sel:DWORD dst_unused:UNUSED_PAD src0_sel:WORD_1 src1_sel:DWORD
	v_add3_u32 v67, v67, v108, s17
	v_add3_u32 v143, v66, v109, s17
	v_and_b32_sdwa v108, v69, v134 dst_sel:DWORD dst_unused:UNUSED_PAD src0_sel:WORD_1 src1_sel:DWORD
	v_and_b32_sdwa v109, v68, v134 dst_sel:DWORD dst_unused:UNUSED_PAD src0_sel:WORD_1 src1_sel:DWORD
	v_mov_b32_e32 v110, v91
	v_mov_b32_e32 v111, v95
	v_and_b32_e32 v92, 0xffff0000, v123
	v_and_b32_e32 v96, 0xffff0000, v121
	v_pk_fma_f32 v[88:89], v[20:21], v[88:89], v[118:119]
	v_and_b32_sdwa v118, v87, v134 dst_sel:DWORD dst_unused:UNUSED_PAD src0_sel:WORD_1 src1_sel:DWORD
	v_add3_u32 v73, v73, v112, s17
	v_add3_u32 v142, v72, v113, s17
	v_add3_u32 v69, v69, v108, s17
	v_add3_u32 v144, v68, v109, s17
	v_mov_b32_e32 v108, v90
	v_mov_b32_e32 v109, v94
	v_pk_mul_f32 v[110:111], v[110:111], v[110:111]
	v_mov_b32_e32 v112, v93
	v_mov_b32_e32 v113, v97
	v_and_b32_sdwa v119, v86, v134 dst_sel:DWORD dst_unused:UNUSED_PAD src0_sel:WORD_1 src1_sel:DWORD
	v_add3_u32 v87, v87, v118, s17
	v_and_b32_sdwa v118, v89, v134 dst_sel:DWORD dst_unused:UNUSED_PAD src0_sel:WORD_1 src1_sel:DWORD
	v_pk_mul_f32 v[80:81], v[80:81], v[150:151] op_sel_hi:[1,0]
	v_pk_fma_f32 v[108:109], v[108:109], v[108:109], v[110:111]
	v_mov_b32_e32 v110, v92
	v_mov_b32_e32 v111, v96
	v_pk_mul_f32 v[112:113], v[112:113], v[112:113]
	v_add3_u32 v124, v86, v119, s17
	v_and_b32_sdwa v119, v88, v134 dst_sel:DWORD dst_unused:UNUSED_PAD src0_sel:WORD_1 src1_sel:DWORD
	v_add3_u32 v89, v89, v118, s17
	v_pk_fma_f32 v[80:81], v[28:29], v[80:81], v[116:117]
	v_and_b32_sdwa v117, v78, v134 dst_sel:DWORD dst_unused:UNUSED_PAD src0_sel:WORD_1 src1_sel:DWORD
	v_pk_mul_f32 v[84:85], v[84:85], v[150:151] op_sel_hi:[1,0]
	v_pk_fma_f32 v[110:111], v[110:111], v[110:111], v[112:113]
	v_and_b32_e32 v87, 0xffff0000, v87
	v_add3_u32 v125, v88, v119, s17
	v_and_b32_e32 v89, 0xffff0000, v89
	v_and_b32_sdwa v116, v79, v134 dst_sel:DWORD dst_unused:UNUSED_PAD src0_sel:WORD_1 src1_sel:DWORD
	v_add3_u32 v135, v78, v117, s17
	v_and_b32_sdwa v117, v80, v134 dst_sel:DWORD dst_unused:UNUSED_PAD src0_sel:WORD_1 src1_sel:DWORD
	v_pk_fma_f32 v[84:85], v[36:37], v[84:85], v[114:115]
	v_and_b32_sdwa v114, v83, v134 dst_sel:DWORD dst_unused:UNUSED_PAD src0_sel:WORD_1 src1_sel:DWORD
	v_and_b32_sdwa v115, v82, v134 dst_sel:DWORD dst_unused:UNUSED_PAD src0_sel:WORD_1 src1_sel:DWORD
	v_pk_add_f32 v[108:109], v[108:109], v[110:111]
	v_and_b32_e32 v86, 0xffff0000, v124
	v_and_b32_e32 v88, 0xffff0000, v125
	v_add3_u32 v79, v79, v116, s17
	v_and_b32_e32 v78, 0xffff0000, v135
	v_and_b32_sdwa v116, v81, v134 dst_sel:DWORD dst_unused:UNUSED_PAD src0_sel:WORD_1 src1_sel:DWORD
	v_add3_u32 v136, v80, v117, s17
	v_add3_u32 v83, v83, v114, s17
	v_add3_u32 v137, v82, v115, s17
	v_and_b32_sdwa v114, v85, v134 dst_sel:DWORD dst_unused:UNUSED_PAD src0_sel:WORD_1 src1_sel:DWORD
	v_and_b32_sdwa v115, v84, v134 dst_sel:DWORD dst_unused:UNUSED_PAD src0_sel:WORD_1 src1_sel:DWORD
	v_pk_add_f32 v[108:109], v[108:109], v[108:109] op_sel_hi:[0,1]
	v_mov_b32_e32 v112, v87
	v_mov_b32_e32 v113, v89
	v_and_b32_e32 v79, 0xffff0000, v79
	v_add3_u32 v81, v81, v116, s17
	v_and_b32_e32 v80, 0xffff0000, v136
	v_add3_u32 v85, v85, v114, s17
	v_add3_u32 v138, v84, v115, s17
	v_mov_b32_e32 v110, v86
; #define GAS __attribute__((address_space(1)))
; __device__ __forceinline__ unsigned pk2(float lo, float hi) { return f2bf(lo) | (f2bf(hi) << 16); }
; __device__ __forceinline__ float bflo(unsigned w) { return __uint_as_float(w << 16); }
; __device__ __forceinline__ float bfhi(unsigned w) { return __uint_as_float(w & 0xffff0000u); }
; __device__ __forceinline__ float dot4(f32x4 a, f32x4 b) { return (a[0] * b[0] + a[1] * b[1]) + (a[2] * b[2] + a[3] * b[3]); }
;     ...
;                 else { v2u w; w.x = pk2(v[j][0], v[j][1]); w.y = pk2(v[j][2], v[j][3]); ((GAS v2u*)(Hout + (size_t)r * D))[lane + 64 * j] = w;
;                        v[j] = (f32x4){bflo(w.x), bfhi(w.x), bflo(w.y), bfhi(w.y)}; } }
;         }
;         if (MODE != 2) {
;             float ss = 0.f;
; #pragma unroll
;             for (int j = 0; j < 8; ++j) ss += dot4(v[j], v[j]);
;             ss = wave_sum(ss);
;             const float rs = 1.0f / sqrtf(ss * (1.0f / D) + EPS);
	v_mov_b32_e32 v111, v88
	v_pk_mul_f32 v[112:113], v[112:113], v[112:113]
	v_mul_f32_e32 v108, v78, v78
	v_and_b32_e32 v81, 0xffff0000, v81
	v_and_b32_e32 v83, 0xffff0000, v83
	v_and_b32_e32 v82, 0xffff0000, v137
	v_and_b32_e32 v85, 0xffff0000, v85
	v_and_b32_e32 v84, 0xffff0000, v138
	v_pk_fma_f32 v[110:111], v[110:111], v[110:111], v[112:113]
	v_pk_fma_f32 v[112:113], v[78:79], v[78:79], v[108:109] op_sel_hi:[1,1,0]
	v_mul_f32_e32 v108, v80, v80
	v_pk_add_f32 v[110:111], v[110:111], v[110:111] op_sel_hi:[0,1]
	v_pk_fma_f32 v[114:115], v[80:81], v[80:81], v[108:109] op_sel_hi:[1,1,0]
	v_pk_mul_f32 v[116:117], v[82:83], v[82:83]
	v_pk_mul_f32 v[118:119], v[84:85], v[84:85]
	v_mov_b32_e32 v112, v116
	v_mov_b32_e32 v114, v117
	v_mov_b32_e32 v110, v118
	v_mov_b32_e32 v108, v119
	v_pk_add_f32 v[112:113], v[112:113], v[114:115]
	v_pk_add_f32 v[108:109], v[110:111], v[108:109]
	v_and_b32_e32 v75, 0xffff0000, v75
	v_and_b32_e32 v77, 0xffff0000, v77
	v_pk_add_f32 v[108:109], v[112:113], v[108:109]
	v_and_b32_e32 v74, 0xffff0000, v139
	v_and_b32_e32 v76, 0xffff0000, v140
	v_and_b32_e32 v70, 0xffff0000, v141
	v_pk_add_f32 v[108:109], v[108:109], v[108:109] op_sel_hi:[0,1]
	v_mov_b32_e32 v112, v75
	v_mov_b32_e32 v113, v77
	v_and_b32_e32 v71, 0xffff0000, v71
	v_and_b32_e32 v72, 0xffff0000, v142
	v_mov_b32_e32 v110, v74
	v_mov_b32_e32 v111, v76
	v_pk_mul_f32 v[112:113], v[112:113], v[112:113]
	v_mul_f32_e32 v108, v70, v70
	v_and_b32_e32 v73, 0xffff0000, v73
	v_and_b32_e32 v67, 0xffff0000, v67
	v_and_b32_e32 v66, 0xffff0000, v143
	v_and_b32_e32 v69, 0xffff0000, v69
	v_and_b32_e32 v68, 0xffff0000, v144
	v_pk_fma_f32 v[110:111], v[110:111], v[110:111], v[112:113]
	v_pk_fma_f32 v[112:113], v[70:71], v[70:71], v[108:109] op_sel_hi:[1,1,0]
	v_mul_f32_e32 v108, v72, v72
	v_pk_add_f32 v[110:111], v[110:111], v[110:111] op_sel_hi:[0,1]
	v_pk_fma_f32 v[114:115], v[72:73], v[72:73], v[108:109] op_sel_hi:[1,1,0]
	v_pk_mul_f32 v[116:117], v[66:67], v[66:67]
	v_pk_mul_f32 v[118:119], v[68:69], v[68:69]
	v_mov_b32_e32 v112, v116
	v_mov_b32_e32 v114, v117
	v_mov_b32_e32 v110, v118
	v_mov_b32_e32 v108, v119
	v_pk_add_f32 v[112:113], v[112:113], v[114:115]
	v_pk_add_f32 v[108:109], v[110:111], v[108:109]
	v_or_b32_sdwa v110, v91, v122 dst_sel:DWORD dst_unused:UNUSED_PAD src0_sel:DWORD src1_sel:WORD_1
	v_pk_add_f32 v[108:109], v[112:113], v[108:109]
	v_or_b32_sdwa v111, v93, v123 dst_sel:DWORD dst_unused:UNUSED_PAD src0_sel:DWORD src1_sel:WORD_1
	v_add_f32_e32 v108, v108, v109
	ds_bpermute_b32 v109, v126, v108
	s_waitcnt lgkmcnt(0)
	v_add_f32_e32 v112, v108, v109
	ds_bpermute_b32 v113, v127, v112
	v_lshl_add_u64 v[108:109], v[98:99], 0, s[10:11]
	global_store_dwordx2 v[108:109], v[110:111], off
	v_or_b32_sdwa v110, v95, v120 dst_sel:DWORD dst_unused:UNUSED_PAD src0_sel:DWORD src1_sel:WORD_1
	v_or_b32_sdwa v111, v97, v121 dst_sel:DWORD dst_unused:UNUSED_PAD src0_sel:DWORD src1_sel:WORD_1
	s_waitcnt lgkmcnt(0)
	v_add_f32_e32 v112, v112, v113
	ds_bpermute_b32 v113, v128, v112
	global_store_dwordx2 v[108:109], v[110:111], off offset:512
	v_or_b32_sdwa v110, v87, v124 dst_sel:DWORD dst_unused:UNUSED_PAD src0_sel:DWORD src1_sel:WORD_1
	v_or_b32_sdwa v111, v89, v125 dst_sel:DWORD dst_unused:UNUSED_PAD src0_sel:DWORD src1_sel:WORD_1
	global_store_dwordx2 v[108:109], v[110:111], off offset:1024
	s_waitcnt lgkmcnt(0)
	v_add_f32_e32 v112, v112, v113
	ds_bpermute_b32 v113, v129, v112
	v_or_b32_sdwa v110, v79, v135 dst_sel:DWORD dst_unused:UNUSED_PAD src0_sel:DWORD src1_sel:WORD_1
	v_or_b32_sdwa v111, v81, v136 dst_sel:DWORD dst_unused:UNUSED_PAD src0_sel:DWORD src1_sel:WORD_1
	global_store_dwordx2 v[108:109], v[110:111], off offset:1536
	v_or_b32_sdwa v110, v83, v137 dst_sel:DWORD dst_unused:UNUSED_PAD src0_sel:DWORD src1_sel:WORD_1
	s_waitcnt lgkmcnt(0)
	v_add_f32_e32 v112, v112, v113
	ds_bpermute_b32 v113, v130, v112
	v_or_b32_sdwa v111, v85, v138 dst_sel:DWORD dst_unused:UNUSED_PAD src0_sel:DWORD src1_sel:WORD_1
	global_store_dwordx2 v[108:109], v[110:111], off offset:2048
	v_or_b32_sdwa v110, v75, v139 dst_sel:DWORD dst_unused:UNUSED_PAD src0_sel:DWORD src1_sel:WORD_1
	v_or_b32_sdwa v111, v77, v140 dst_sel:DWORD dst_unused:UNUSED_PAD src0_sel:DWORD src1_sel:WORD_1
	s_waitcnt lgkmcnt(0)
	v_add_f32_e32 v112, v112, v113
	ds_bpermute_b32 v113, v131, v112
	global_store_dwordx2 v[108:109], v[110:111], off offset:2560
	s_waitcnt lgkmcnt(0)
; #define GAS __attribute__((address_space(1)))
; __device__ __forceinline__ unsigned pk2(float lo, float hi) { return f2bf(lo) | (f2bf(hi) << 16); }
;     ...
;             const float rs = 1.0f / sqrtf(ss * (1.0f / D) + EPS);
;             float ga[8];
; #pragma unroll
;             for (int c = 0; c < 8; ++c) ga[c] = 0.f;
;             GAS v2u* op = (GAS v2u*)(XN + (size_t)r * D) + lane;
; #pragma unroll
;             for (int j = 0; j < 8; ++j) { const f32x4 g = gpr[j]; const f32x4 xn = (v[j] * rs) * g;
;                 v2u w; w.x = pk2(xn[0], xn[1]); w.y = pk2(xn[2], xn[3]); op[64 * j] = w;
	v_add_f32_e32 v110, v112, v113
	v_fmamk_f32 v110, v110, 0x3a000000, v132
	v_mul_f32_e32 v111, 0x4f800000, v110
	v_cmp_gt_f32_e32 vcc, s16, v110
	s_nop 1
	v_cndmask_b32_e32 v112, v110, v111, vcc
	v_sqrt_f32_e32 v113, v112
	v_or_b32_sdwa v110, v71, v141 dst_sel:DWORD dst_unused:UNUSED_PAD src0_sel:DWORD src1_sel:WORD_1
	v_or_b32_sdwa v111, v73, v142 dst_sel:DWORD dst_unused:UNUSED_PAD src0_sel:DWORD src1_sel:WORD_1
	global_store_dwordx2 v[108:109], v[110:111], off offset:3072
	v_add_u32_e32 v110, -1, v113
	v_fma_f32 v111, -v110, v113, v112
	v_cmp_ge_f32_e64 s[0:1], 0, v111
	v_add_u32_e32 v111, 1, v113
	s_nop 0
	v_cndmask_b32_e64 v110, v113, v110, s[0:1]
	v_fma_f32 v113, -v111, v113, v112
	v_cmp_lt_f32_e64 s[0:1], 0, v113
	s_nop 1
	v_cndmask_b32_e64 v110, v110, v111, s[0:1]
	v_mul_f32_e32 v111, 0x37800000, v110
	v_cndmask_b32_e32 v110, v110, v111, vcc
	v_cmp_class_f32_e32 vcc, v112, v133
	v_or_b32_sdwa v111, v69, v144 dst_sel:DWORD dst_unused:UNUSED_PAD src0_sel:DWORD src1_sel:WORD_1
	s_nop 0
	v_cndmask_b32_e32 v112, v110, v112, vcc
	v_div_scale_f32 v113, s[0:1], v112, v112, 1.0
	v_rcp_f32_e32 v114, v113
	v_or_b32_sdwa v110, v67, v143 dst_sel:DWORD dst_unused:UNUSED_PAD src0_sel:DWORD src1_sel:WORD_1
	global_store_dwordx2 v[108:109], v[110:111], off offset:3584
	v_fma_f32 v108, -v113, v114, 1.0
	v_fmac_f32_e32 v114, v108, v114
	v_div_scale_f32 v108, vcc, 1.0, v112, 1.0
	v_mul_f32_e32 v109, v108, v114
	v_fma_f32 v110, -v113, v109, v108
	v_fmac_f32_e32 v109, v110, v114
	v_fma_f32 v108, -v113, v109, v108
	v_div_fmas_f32 v108, v108, v114, v109
	v_div_fixup_f32 v108, v108, v112, 1.0
	v_pk_mul_f32 v[90:91], v[108:109], v[90:91] op_sel_hi:[0,1]
	v_pk_mul_f32 v[90:91], v[6:7], v[90:91]
	v_pk_mul_f32 v[92:93], v[108:109], v[92:93] op_sel_hi:[0,1]
	v_bfe_u32 v109, v90, 16, 1
	v_add3_u32 v90, v90, v109, s17
	v_bfe_u32 v109, v91, 16, 1
	v_pk_mul_f32 v[92:93], v[8:9], v[92:93]
	v_lshrrev_b32_e32 v90, 16, v90
	v_add3_u32 v91, v91, v109, s17
	v_and_or_b32 v90, v91, s14, v90
	v_bfe_u32 v91, v92, 16, 1
	v_add3_u32 v91, v92, v91, s17
	v_bfe_u32 v92, v93, 16, 1
	v_lshrrev_b32_e32 v91, 16, v91
	v_add3_u32 v92, v93, v92, s17
	v_lshl_add_u64 v[110:111], v[106:107], 0, s[10:11]
	v_and_or_b32 v91, v92, s14, v91
	global_store_dwordx2 v[110:111], v[90:91], off
	v_pk_mul_f32 v[90:91], v[108:109], v[94:95] op_sel_hi:[0,1]
	v_pk_mul_f32 v[90:91], v[14:15], v[90:91]
	v_pk_mul_f32 v[92:93], v[108:109], v[96:97] op_sel_hi:[0,1]
	v_bfe_u32 v94, v90, 16, 1
	v_add3_u32 v90, v90, v94, s17
	v_bfe_u32 v94, v91, 16, 1
	v_pk_mul_f32 v[92:93], v[16:17], v[92:93]
	v_lshrrev_b32_e32 v90, 16, v90
	v_add3_u32 v91, v91, v94, s17
	v_and_or_b32 v90, v91, s14, v90
	v_bfe_u32 v91, v92, 16, 1
	v_add3_u32 v91, v92, v91, s17
	v_bfe_u32 v92, v93, 16, 1
	v_lshrrev_b32_e32 v91, 16, v91
	v_add3_u32 v92, v93, v92, s17
	v_pk_mul_f32 v[86:87], v[108:109], v[86:87] op_sel_hi:[0,1]
	v_and_or_b32 v91, v92, s14, v91
	v_pk_mul_f32 v[86:87], v[22:23], v[86:87]
	global_store_dwordx2 v[110:111], v[90:91], off offset:512
	v_bfe_u32 v90, v86, 16, 1
	v_pk_mul_f32 v[88:89], v[108:109], v[88:89] op_sel_hi:[0,1]
	v_add3_u32 v86, v86, v90, s17
	v_bfe_u32 v90, v87, 16, 1
	v_pk_mul_f32 v[88:89], v[24:25], v[88:89]
	v_lshrrev_b32_e32 v86, 16, v86
	v_add3_u32 v87, v87, v90, s17
	v_and_or_b32 v86, v87, s14, v86
	v_bfe_u32 v87, v88, 16, 1
	v_add3_u32 v87, v88, v87, s17
	v_bfe_u32 v88, v89, 16, 1
	v_lshrrev_b32_e32 v87, 16, v87
	v_add3_u32 v88, v89, v88, s17
	v_pk_mul_f32 v[78:79], v[108:109], v[78:79] op_sel_hi:[0,1]
	v_and_or_b32 v87, v88, s14, v87
	v_pk_mul_f32 v[78:79], v[30:31], v[78:79]
	global_store_dwordx2 v[110:111], v[86:87], off offset:1024
	v_bfe_u32 v86, v78, 16, 1
	v_pk_mul_f32 v[80:81], v[108:109], v[80:81] op_sel_hi:[0,1]
	v_add3_u32 v78, v78, v86, s17
	v_bfe_u32 v86, v79, 16, 1
	v_pk_mul_f32 v[80:81], v[32:33], v[80:81]
	v_lshrrev_b32_e32 v78, 16, v78
	v_add3_u32 v79, v79, v86, s17
	v_and_or_b32 v78, v79, s14, v78
	v_bfe_u32 v79, v80, 16, 1
	v_add3_u32 v79, v80, v79, s17
	v_bfe_u32 v80, v81, 16, 1
	v_lshrrev_b32_e32 v79, 16, v79
	v_add3_u32 v80, v81, v80, s17
	v_and_or_b32 v79, v80, s14, v79
	global_store_dwordx2 v[110:111], v[78:79], off offset:1536
	v_pk_mul_f32 v[78:79], v[108:109], v[82:83] op_sel_hi:[0,1]
	v_pk_mul_f32 v[78:79], v[38:39], v[78:79]
	v_pk_mul_f32 v[80:81], v[108:109], v[84:85] op_sel_hi:[0,1]
	v_bfe_u32 v82, v78, 16, 1
	v_add3_u32 v78, v78, v82, s17
	v_bfe_u32 v82, v79, 16, 1
	v_pk_mul_f32 v[80:81], v[40:41], v[80:81]
	v_lshrrev_b32_e32 v78, 16, v78
	v_add3_u32 v79, v79, v82, s17
	v_and_or_b32 v78, v79, s14, v78
	v_bfe_u32 v79, v80, 16, 1
	v_add3_u32 v79, v80, v79, s17
	v_bfe_u32 v80, v81, 16, 1
	v_lshrrev_b32_e32 v79, 16, v79
	v_add3_u32 v80, v81, v80, s17
	v_pk_mul_f32 v[74:75], v[108:109], v[74:75] op_sel_hi:[0,1]
	v_and_or_b32 v79, v80, s14, v79
	v_pk_mul_f32 v[74:75], v[46:47], v[74:75]
	global_store_dwordx2 v[110:111], v[78:79], off offset:2048
	v_bfe_u32 v78, v74, 16, 1
	v_pk_mul_f32 v[76:77], v[108:109], v[76:77] op_sel_hi:[0,1]
	v_add3_u32 v74, v74, v78, s17
	v_bfe_u32 v78, v75, 16, 1
	v_pk_mul_f32 v[76:77], v[48:49], v[76:77]
	v_lshrrev_b32_e32 v74, 16, v74
	v_add3_u32 v75, v75, v78, s17
	v_and_or_b32 v74, v75, s14, v74
	v_bfe_u32 v75, v76, 16, 1
	v_add3_u32 v75, v76, v75, s17
	v_bfe_u32 v76, v77, 16, 1
	v_lshrrev_b32_e32 v75, 16, v75
	v_add3_u32 v76, v77, v76, s17
	v_pk_mul_f32 v[70:71], v[108:109], v[70:71] op_sel_hi:[0,1]
	v_and_or_b32 v75, v76, s14, v75
	v_pk_mul_f32 v[70:71], v[54:55], v[70:71]
	global_store_dwordx2 v[110:111], v[74:75], off offset:2560
	v_bfe_u32 v74, v70, 16, 1
	v_pk_mul_f32 v[72:73], v[108:109], v[72:73] op_sel_hi:[0,1]
	v_add3_u32 v70, v70, v74, s17
	v_bfe_u32 v74, v71, 16, 1
	v_pk_mul_f32 v[72:73], v[56:57], v[72:73]
	v_lshrrev_b32_e32 v70, 16, v70
	v_add3_u32 v71, v71, v74, s17
	v_and_or_b32 v70, v71, s14, v70
	v_bfe_u32 v71, v72, 16, 1
	v_add3_u32 v71, v72, v71, s17
	v_bfe_u32 v72, v73, 16, 1
	v_lshrrev_b32_e32 v71, 16, v71
	v_add3_u32 v72, v73, v72, s17
	v_pk_mul_f32 v[66:67], v[108:109], v[66:67] op_sel_hi:[0,1]
	v_and_or_b32 v71, v72, s14, v71
	v_pk_mul_f32 v[66:67], v[62:63], v[66:67]
	global_store_dwordx2 v[110:111], v[70:71], off offset:3072
	v_bfe_u32 v70, v66, 16, 1
	v_pk_mul_f32 v[68:69], v[108:109], v[68:69] op_sel_hi:[0,1]
	v_add3_u32 v66, v66, v70, s17
	v_bfe_u32 v70, v67, 16, 1
	v_pk_mul_f32 v[68:69], v[64:65], v[68:69]
	v_lshrrev_b32_e32 v66, 16, v66
	v_add3_u32 v67, v67, v70, s17
	v_and_or_b32 v66, v67, s14, v66
	v_bfe_u32 v67, v68, 16, 1
	v_add3_u32 v67, v68, v67, s17
	v_bfe_u32 v68, v69, 16, 1
	v_lshrrev_b32_e32 v67, 16, v67
	v_add3_u32 v68, v69, v68, s17
	v_and_or_b32 v67, v68, s14, v67
	global_store_dwordx2 v[110:111], v[66:67], off offset:3584
	s_cbranch_scc0 .LBB0_1758
; #define GAS __attribute__((address_space(1)))
; __device__ __forceinline__ float bflo(unsigned w) { return __uint_as_float(w << 16); }
; __device__ __forceinline__ float bfhi(unsigned w) { return __uint_as_float(w & 0xffff0000u); }
; __device__ __forceinline__ float sigmf(float x) { return __builtin_amdgcn_rcpf(1.0f + __expf(-x)); }
; __device__ __forceinline__ float dot4(f32x4 a, f32x4 b) { return (a[0] * b[0] + a[1] * b[1]) + (a[2] * b[2] + a[3] * b[3]); }
;     ...
;     for (int r = gw; r < M; r += NGW) {
;         f32x4 v[8];
;         if (RES) { const GAS v2u* rp = (const GAS v2u*)(RES + (size_t)r * D) + lane;
; #pragma unroll
;             for (int j = 0; j < 8; ++j) { const v2u w = rp[64 * j]; v[j] = (f32x4){bflo(w.x), bfhi(w.x), bflo(w.y), bfhi(w.y)}; } }
;         else { const GAS f32x4* rp = (const GAS f32x4*)xrow(a, r) + lane;
; #pragma unroll
;             for (int j = 0; j < 8; ++j) v[j] = rp[64 * j]; }
;         if (MODE != 0) {
;             const GAS v2u* tp = (const GAS v2u*)(T + (size_t)r * D) + lane;
;             f32x4 t[8]; float ss = 0.f;
;             if (TSRC != 0 && r >= NP) {
;                 const GAS f32x4* sp = (const GAS f32x4*)(WSP(float, WS_SLAB) + (size_t)(r - NP) * D) + lane;
; #pragma unroll
;                 for (int j = 0; j < 8; ++j) t[j] = sp[64 * j];
;                 _Pragma("unroll 1") for (int s = 1; s < nslab; ++s) { sp += (size_t)NS * D / 4;
; #pragma unroll
;                     for (int j = 0; j < 8; ++j) t[j] += sp[64 * j]; }
;                 if (TSRC == 2) { const GAS v2u* pp = (const GAS v2u*)(PUP + (size_t)r * D) + lane;
; #pragma unroll
;                     for (int j = 0; j < 8; ++j) { const v2u pw = pp[64 * j]; const f32x4 p = (f32x4){bflo(pw.x), bfhi(pw.x), bflo(pw.y), bfhi(pw.y)}; t[j] = (f32x4){sigmf(t[j][0]), sigmf(t[j][1]), sigmf(t[j][2]), sigmf(t[j][3])} * p; } }
; #pragma unroll
;                 for (int j = 0; j < 8; ++j) ss += dot4(t[j], t[j]);
;             } else {
; #pragma unroll
;                 for (int j = 0; j < 8; ++j) { const v2u tw = tp[64 * j]; t[j] = (f32x4){bflo(tw.x), bfhi(tw.x), bflo(tw.y), bfhi(tw.y)}; ss += dot4(t[j], t[j]); }
.LBB0_1752:
	s_cmp_lt_i32 s6, s3
	s_cbranch_scc1 .Lrowpf1752_orig
	s_cmpk_gt_i32 s6, 0x1fff
	s_cbranch_scc1 .Lrowpf1752_orig
	s_waitcnt vmcnt(16)
	s_ashr_i32 s7, s6, 31
	s_lshl_b64 s[0:1], s[6:7], 12
	v_lshl_add_u64 v[66:67], v[98:99], 0, s[0:1]
	v_mov_b32_e32 v122, v168
	v_mov_b32_e32 v123, v169
	v_mov_b32_e32 v120, v170
	v_mov_b32_e32 v121, v171
	v_mov_b32_e32 v118, v172
	v_mov_b32_e32 v119, v173
	v_mov_b32_e32 v116, v174
	v_mov_b32_e32 v117, v175
	v_mov_b32_e32 v114, v176
	v_mov_b32_e32 v115, v177
	v_mov_b32_e32 v112, v178
	v_mov_b32_e32 v113, v179
	v_mov_b32_e32 v110, v180
	v_mov_b32_e32 v111, v181
	v_mov_b32_e32 v108, v182
	v_mov_b32_e32 v109, v183
	s_lshl_b64 s[10:11], s[6:7], 11
	s_cmpk_gt_i32 s6, 0x1fff
	s_mov_b64 s[0:1], -1
	v_lshl_add_u64 v[66:67], s[10:11], 1, v[100:101]
	v_mov_b32_e32 v68, v184
	v_mov_b32_e32 v69, v185
	v_mov_b32_e32 v70, v186
	v_mov_b32_e32 v71, v187
	v_mov_b32_e32 v72, v188
	v_mov_b32_e32 v73, v189
	v_mov_b32_e32 v74, v190
	v_mov_b32_e32 v75, v191
	v_mov_b32_e32 v76, v192
	v_mov_b32_e32 v77, v193
	v_mov_b32_e32 v82, v194
	v_mov_b32_e32 v83, v195
	v_mov_b32_e32 v84, v196
	v_mov_b32_e32 v85, v197
	v_mov_b32_e32 v94, v198
	v_mov_b32_e32 v95, v199
	s_mov_b64 s[0:1], 0
	s_branch .Lrowpf1752_conv

; #define GAS __attribute__((address_space(1)))
; __device__ __forceinline__ float bflo(unsigned w) { return __uint_as_float(w << 16); }
; __device__ __forceinline__ float bfhi(unsigned w) { return __uint_as_float(w & 0xffff0000u); }
; __device__ __forceinline__ float sigmf(float x) { return __builtin_amdgcn_rcpf(1.0f + __expf(-x)); }
; __device__ __forceinline__ float dot4(f32x4 a, f32x4 b) { return (a[0] * b[0] + a[1] * b[1]) + (a[2] * b[2] + a[3] * b[3]); }
;     ...
;     for (int r = gw; r < M; r += NGW) {
;         f32x4 v[8];
;         if (RES) { const GAS v2u* rp = (const GAS v2u*)(RES + (size_t)r * D) + lane;
; #pragma unroll
;             for (int j = 0; j < 8; ++j) { const v2u w = rp[64 * j]; v[j] = (f32x4){bflo(w.x), bfhi(w.x), bflo(w.y), bfhi(w.y)}; } }
;         else { const GAS f32x4* rp = (const GAS f32x4*)xrow(a, r) + lane;
; #pragma unroll
;             for (int j = 0; j < 8; ++j) v[j] = rp[64 * j]; }
;         if (MODE != 0) {
;             const GAS v2u* tp = (const GAS v2u*)(T + (size_t)r * D) + lane;
;             f32x4 t[8]; float ss = 0.f;
;             if (TSRC != 0 && r >= NP) {
;                 const GAS f32x4* sp = (const GAS f32x4*)(WSP(float, WS_SLAB) + (size_t)(r - NP) * D) + lane;
; #pragma unroll
;                 for (int j = 0; j < 8; ++j) t[j] = sp[64 * j];
;                 _Pragma("unroll 1") for (int s = 1; s < nslab; ++s) { sp += (size_t)NS * D / 4;
; #pragma unroll
;                     for (int j = 0; j < 8; ++j) t[j] += sp[64 * j]; }
;                 if (TSRC == 2) { const GAS v2u* pp = (const GAS v2u*)(PUP + (size_t)r * D) + lane;
; #pragma unroll
;                     for (int j = 0; j < 8; ++j) { const v2u pw = pp[64 * j]; const f32x4 p = (f32x4){bflo(pw.x), bfhi(pw.x), bflo(pw.y), bfhi(pw.y)}; t[j] = (f32x4){sigmf(t[j][0]), sigmf(t[j][1]), sigmf(t[j][2]), sigmf(t[j][3])} * p; } }
; #pragma unroll
;                 for (int j = 0; j < 8; ++j) ss += dot4(t[j], t[j]);
;             } else {
; #pragma unroll
;                 for (int j = 0; j < 8; ++j) { const v2u tw = tp[64 * j]; t[j] = (f32x4){bflo(tw.x), bfhi(tw.x), bflo(tw.y), bfhi(tw.y)}; ss += dot4(t[j], t[j]); }
.LBB0_1898:
	ds_bpermute_b32 v91, v92, v90
	s_add_i32 s60, s2, s8
	s_cmpk_gt_i32 s60, 0x1fff
	s_cbranch_scc1 .Lrowpf1899_skip
	s_lshl_b32 s60, s60, 12
	s_mov_b32 s61, 0
	v_lshl_add_u64 v[170:171], v[64:65], 0, s[60:61]
	global_load_dwordx2 v[138:139], v[170:171], off
	global_load_dwordx2 v[140:141], v[170:171], off offset:512
	global_load_dwordx2 v[142:143], v[170:171], off offset:1024
	global_load_dwordx2 v[144:145], v[170:171], off offset:1536
	global_load_dwordx2 v[146:147], v[170:171], off offset:2048
	global_load_dwordx2 v[148:149], v[170:171], off offset:2560
	global_load_dwordx2 v[150:151], v[170:171], off offset:3072
	global_load_dwordx2 v[152:153], v[170:171], off offset:3584
	s_nop 0
	v_lshl_add_u64 v[170:171], v[66:67], 0, s[60:61]
	global_load_dwordx2 v[154:155], v[170:171], off
	global_load_dwordx2 v[156:157], v[170:171], off offset:512
	global_load_dwordx2 v[158:159], v[170:171], off offset:1024
	global_load_dwordx2 v[160:161], v[170:171], off offset:1536
	global_load_dwordx2 v[162:163], v[170:171], off offset:2048
	global_load_dwordx2 v[164:165], v[170:171], off offset:2560
	global_load_dwordx2 v[166:167], v[170:171], off offset:3072
	global_load_dwordx2 v[168:169], v[170:171], off offset:3584
; #define GAS __attribute__((address_space(1)))
; __device__ __forceinline__ float bflo(unsigned w) { return __uint_as_float(w << 16); }
; __device__ __forceinline__ float bfhi(unsigned w) { return __uint_as_float(w & 0xffff0000u); }
; __device__ __forceinline__ float sigmf(float x) { return __builtin_amdgcn_rcpf(1.0f + __expf(-x)); }
;     ...
;     for (int r = gw; r < M; r += NGW) {
;         f32x4 v[8];
;         if (RES) { const GAS v2u* rp = (const GAS v2u*)(RES + (size_t)r * D) + lane;
; #pragma unroll
;             for (int j = 0; j < 8; ++j) { const v2u w = rp[64 * j]; v[j] = (f32x4){bflo(w.x), bfhi(w.x), bflo(w.y), bfhi(w.y)}; } }
;         else { const GAS f32x4* rp = (const GAS f32x4*)xrow(a, r) + lane;
; #pragma unroll
;             for (int j = 0; j < 8; ++j) v[j] = rp[64 * j]; }
;         if (MODE != 0) {
;             const GAS v2u* tp = (const GAS v2u*)(T + (size_t)r * D) + lane;
;             f32x4 t[8]; float ss = 0.f;
;             if (TSRC != 0 && r >= NP) {
;                 const GAS f32x4* sp = (const GAS f32x4*)(WSP(float, WS_SLAB) + (size_t)(r - NP) * D) + lane;
; #pragma unroll
;                 for (int j = 0; j < 8; ++j) t[j] = sp[64 * j];
;                 _Pragma("unroll 1") for (int s = 1; s < nslab; ++s) { sp += (size_t)NS * D / 4;
; #pragma unroll
;                     for (int j = 0; j < 8; ++j) t[j] += sp[64 * j]; }
;                 if (TSRC == 2) { const GAS v2u* pp = (const GAS v2u*)(PUP + (size_t)r * D) + lane;
; #pragma unroll
;                     for (int j = 0; j < 8; ++j) { const v2u pw = pp[64 * j]; const f32x4 p = (f32x4){bflo(pw.x), bfhi(pw.x), bflo(pw.y), bfhi(pw.y)}; t[j] = (f32x4){sigmf(t[j][0]), sigmf(t[j][1]), sigmf(t[j][2]), sigmf(t[j][3])} * p; } }
; #pragma unroll
;                 for (int j = 0; j < 8; ++j) ss += dot4(t[j], t[j]);
;             } else {
; #pragma unroll
;                 for (int j = 0; j < 8; ++j) { const v2u tw = tp[64 * j]; t[j] = (f32x4){bflo(tw.x), bfhi(tw.x), bflo(tw.y), bfhi(tw.y)}; ss += dot4(t[j], t[j]); }
;     ...
;             ss = wave_sum(ss);
;             const float rs = sc * (1.0f / sqrtf(ss * (1.0f / D) + EPS));
; #pragma unroll
;             for (int j = 0; j < 8; ++j) { const f32x4 g = gpo[j]; v[j] = v[j] + (t[j] * rs) * g;
;                 if (MODE == 2) ((GAS f32x4*)(Yout + (size_t)r * D))[lane + 64 * j] = v[j];
.Lrowpf1899_skip:
	v_and_b32_e32 v117, 0xffff0000, v76
	v_and_b32_e32 v115, 0xffff0000, v78
	v_lshlrev_b32_e32 v106, 16, v88
	v_and_b32_e32 v107, 0xffff0000, v88
	s_waitcnt lgkmcnt(0)
	v_add_f32_e32 v105, v90, v91
	ds_bpermute_b32 v110, v93, v105
	v_lshlrev_b32_e32 v88, 16, v89
	v_and_b32_e32 v89, 0xffff0000, v89
	v_lshlrev_b32_e32 v108, 16, v86
	v_and_b32_e32 v109, 0xffff0000, v86
	s_waitcnt lgkmcnt(0)
	v_add_f32_e32 v105, v105, v110
	ds_bpermute_b32 v112, v94, v105
	v_lshlrev_b32_e32 v86, 16, v87
	v_and_b32_e32 v87, 0xffff0000, v87
	v_lshlrev_b32_e32 v90, 16, v84
	v_and_b32_e32 v91, 0xffff0000, v84
	s_waitcnt lgkmcnt(0)
	v_add_f32_e32 v105, v105, v112
	ds_bpermute_b32 v114, v95, v105
	v_lshlrev_b32_e32 v84, 16, v85
	v_and_b32_e32 v85, 0xffff0000, v85
	v_lshlrev_b32_e32 v110, 16, v82
	v_and_b32_e32 v111, 0xffff0000, v82
	s_waitcnt lgkmcnt(0)
	v_add_f32_e32 v105, v105, v114
	ds_bpermute_b32 v116, v96, v105
	v_lshlrev_b32_e32 v114, 16, v78
	v_lshlrev_b32_e32 v78, 16, v79
	v_and_b32_e32 v79, 0xffff0000, v79
	v_lshlrev_b32_e32 v82, 16, v83
	s_waitcnt lgkmcnt(0)
	v_add_f32_e32 v105, v105, v116
	ds_bpermute_b32 v118, v97, v105
	v_lshlrev_b32_e32 v116, 16, v76
	v_and_b32_e32 v83, 0xffff0000, v83
	v_lshlrev_b32_e32 v112, 16, v80
	v_and_b32_e32 v113, 0xffff0000, v80
	s_waitcnt lgkmcnt(0)
	v_add_f32_e32 v76, v105, v118
	v_fmamk_f32 v76, v76, 0x3a000000, v98
	v_mul_f32_e32 v105, 0x4f800000, v76
	v_cmp_gt_f32_e32 vcc, s11, v76
	v_lshlrev_b32_e32 v80, 16, v81
	v_and_b32_e32 v81, 0xffff0000, v81
	v_cndmask_b32_e32 v105, v76, v105, vcc
	v_sqrt_f32_e32 v119, v105
	v_lshlrev_b32_e32 v76, 16, v77
	v_and_b32_e32 v77, 0xffff0000, v77
	v_lshlrev_b32_e32 v118, 16, v74
	v_add_u32_e32 v120, -1, v119
	v_fma_f32 v121, -v120, v119, v105
	v_cmp_ge_f32_e64 s[0:1], 0, v121
	v_add_u32_e32 v121, 1, v119
	s_nop 0
	v_cndmask_b32_e64 v120, v119, v120, s[0:1]
	v_fma_f32 v119, -v121, v119, v105
	v_cmp_lt_f32_e64 s[0:1], 0, v119
	s_nop 1
	v_cndmask_b32_e64 v119, v120, v121, s[0:1]
	v_mul_f32_e32 v120, 0x37800000, v119
	v_cndmask_b32_e32 v119, v119, v120, vcc
	v_cmp_class_f32_e32 vcc, v105, v99
	s_nop 1
	v_cndmask_b32_e32 v105, v119, v105, vcc
	v_div_scale_f32 v120, s[0:1], v105, v105, 1.0
	v_rcp_f32_e32 v121, v120
	s_lshl_b64 s[0:1], s[6:7], 2
	s_add_u32 s0, s90, s0
	s_addc_u32 s1, s91, s1
	v_fma_f32 v122, -v120, v121, 1.0
	v_fmac_f32_e32 v121, v122, v121
	v_div_scale_f32 v122, vcc, 1.0, v105, 1.0
	v_mul_f32_e32 v123, v122, v121
	v_fma_f32 v124, -v120, v123, v122
	v_fmac_f32_e32 v123, v124, v121
	v_fma_f32 v120, -v120, v123, v122
	v_div_fmas_f32 v120, v120, v121, v123
	v_div_fixup_f32 v120, v120, v105, 1.0
	v_pk_mul_f32 v[40:41], v[40:41], v[120:121] op_sel_hi:[1,0]
	v_pk_mul_f32 v[42:43], v[42:43], v[120:121] op_sel_hi:[1,0]
	v_pk_mul_f32 v[122:123], v[60:61], v[120:121] op_sel_hi:[1,0]
	v_pk_mul_f32 v[58:59], v[58:59], v[120:121] op_sel_hi:[1,0]
	v_pk_fma_f32 v[42:43], v[22:23], v[42:43], v[78:79]
	v_pk_fma_f32 v[40:41], v[20:21], v[40:41], v[114:115]
	v_pk_fma_f32 v[60:61], v[2:3], v[58:59], v[88:89]
	v_pk_fma_f32 v[58:59], v[0:1], v[122:123], v[106:107]
	global_store_dwordx4 v102, v[40:43], s[0:1]
	v_pk_mul_f32 v[36:37], v[36:37], v[120:121] op_sel_hi:[1,0]
	global_store_dwordx4 v100, v[58:61], s[0:1]
	v_pk_mul_f32 v[40:41], v[38:39], v[120:121] op_sel_hi:[1,0]
	v_pk_mul_f32 v[54:55], v[54:55], v[120:121] op_sel_hi:[1,0]
	v_pk_mul_f32 v[58:59], v[62:63], v[120:121] op_sel_hi:[1,0]
	v_pk_mul_f32 v[48:49], v[48:49], v[120:121] op_sel_hi:[1,0]
	v_pk_fma_f32 v[38:39], v[26:27], v[36:37], v[76:77]
	v_pk_fma_f32 v[36:37], v[24:25], v[40:41], v[116:117]
	v_and_b32_e32 v119, 0xffff0000, v74
	v_lshlrev_b32_e32 v74, 16, v75
	v_and_b32_e32 v75, 0xffff0000, v75
	v_pk_fma_f32 v[60:61], v[6:7], v[58:59], v[86:87]
	v_pk_fma_f32 v[58:59], v[4:5], v[54:55], v[108:109]
	v_pk_mul_f32 v[52:53], v[52:53], v[120:121] op_sel_hi:[1,0]
	v_pk_fma_f32 v[54:55], v[10:11], v[48:49], v[84:85]
	v_pk_mul_f32 v[48:49], v[56:57], v[120:121] op_sel_hi:[1,0]
	v_pk_mul_f32 v[50:51], v[50:51], v[120:121] op_sel_hi:[1,0]
	v_pk_mul_f32 v[44:45], v[44:45], v[120:121] op_sel_hi:[1,0]
	v_pk_mul_f32 v[46:47], v[46:47], v[120:121] op_sel_hi:[1,0]
	global_store_dwordx4 v103, v[36:39], s[0:1]
	v_pk_mul_f32 v[32:33], v[32:33], v[120:121] op_sel_hi:[1,0]
	s_add_i32 s2, s2, s8
	v_pk_mul_f32 v[36:37], v[34:35], v[120:121] op_sel_hi:[1,0]
	s_add_i32 s4, s4, s8
	v_pk_fma_f32 v[52:53], v[8:9], v[52:53], v[90:91]
	v_pk_fma_f32 v[50:51], v[14:15], v[50:51], v[82:83]
	v_pk_fma_f32 v[48:49], v[12:13], v[48:49], v[110:111]
	v_pk_fma_f32 v[46:47], v[18:19], v[46:47], v[80:81]
	v_pk_fma_f32 v[44:45], v[16:17], v[44:45], v[112:113]
	v_pk_fma_f32 v[34:35], v[30:31], v[32:33], v[74:75]
	v_pk_fma_f32 v[32:33], v[28:29], v[36:37], v[118:119]
	s_cmpk_lt_i32 s2, 0x2200
	global_store_dwordx4 v100, v[58:61], s[0:1] offset:1024
	global_store_dwordx4 v100, v[52:55], s[0:1] offset:2048
	global_store_dwordx4 v100, v[48:51], s[0:1] offset:3072
	global_store_dwordx4 v101, v[44:47], s[0:1]
	global_store_dwordx4 v104, v[32:35], s[0:1]
	s_cbranch_scc0 .LBB0_1905
.LBB0_1899:
	s_cmp_lt_i32 s2, s8
	s_cbranch_scc1 .Lrowpf1899_orig
	s_cmpk_gt_i32 s2, 0x1fff
	s_cbranch_scc1 .Lrowpf1899_orig
	s_waitcnt vmcnt(8)
	s_ashr_i32 s3, s2, 31
	s_lshl_b64 s[0:1], s[2:3], 12
	v_lshl_add_u64 v[32:33], v[64:65], 0, s[0:1]
	v_mov_b32_e32 v88, v138
	v_mov_b32_e32 v89, v139
	v_mov_b32_e32 v86, v140
	v_mov_b32_e32 v87, v141
	v_mov_b32_e32 v84, v142
	v_mov_b32_e32 v85, v143
	v_mov_b32_e32 v82, v144
	v_mov_b32_e32 v83, v145
	v_mov_b32_e32 v80, v146
	v_mov_b32_e32 v81, v147
	v_mov_b32_e32 v78, v148
	v_mov_b32_e32 v79, v149
	v_mov_b32_e32 v76, v150
	v_mov_b32_e32 v77, v151
	v_mov_b32_e32 v74, v152
	v_mov_b32_e32 v75, v153
	s_lshl_b64 s[6:7], s[2:3], 11
	s_cmpk_gt_i32 s2, 0x1fff
	s_mov_b64 s[0:1], -1
	v_lshl_add_u64 v[32:33], s[6:7], 1, v[66:67]
	v_mov_b32_e32 v34, v154
	v_mov_b32_e32 v35, v155
	v_mov_b32_e32 v36, v156
	v_mov_b32_e32 v37, v157
	v_mov_b32_e32 v38, v158
	v_mov_b32_e32 v39, v159
	v_mov_b32_e32 v40, v160
	v_mov_b32_e32 v41, v161
	v_mov_b32_e32 v42, v162
	v_mov_b32_e32 v43, v163
	v_mov_b32_e32 v46, v164
	v_mov_b32_e32 v47, v165
	v_mov_b32_e32 v62, v166
	v_mov_b32_e32 v63, v167
	v_mov_b32_e32 v90, v168
	v_mov_b32_e32 v91, v169
	s_mov_b64 s[0:1], 0
	s_branch .Lrowpf1899_conv

; #define GAS __attribute__((address_space(1)))
; __device__ __forceinline__ float bflo(unsigned w) { return __uint_as_float(w << 16); }
; __device__ __forceinline__ float bfhi(unsigned w) { return __uint_as_float(w & 0xffff0000u); }
; __device__ __forceinline__ float sigmf(float x) { return __builtin_amdgcn_rcpf(1.0f + __expf(-x)); }
; __device__ __forceinline__ float dot4(f32x4 a, f32x4 b) { return (a[0] * b[0] + a[1] * b[1]) + (a[2] * b[2] + a[3] * b[3]); }
;     ...
;         if (RES) { const GAS v2u* rp = (const GAS v2u*)(RES + (size_t)r * D) + lane;
; #pragma unroll
;             for (int j = 0; j < 8; ++j) { const v2u w = rp[64 * j]; v[j] = (f32x4){bflo(w.x), bfhi(w.x), bflo(w.y), bfhi(w.y)}; } }
;         else { const GAS f32x4* rp = (const GAS f32x4*)xrow(a, r) + lane;
; #pragma unroll
;             for (int j = 0; j < 8; ++j) v[j] = rp[64 * j]; }
;         if (MODE != 0) {
;             const GAS v2u* tp = (const GAS v2u*)(T + (size_t)r * D) + lane;
;             f32x4 t[8]; float ss = 0.f;
;             if (TSRC != 0 && r >= NP) {
;                 const GAS f32x4* sp = (const GAS f32x4*)(WSP(float, WS_SLAB) + (size_t)(r - NP) * D) + lane;
; #pragma unroll
;                 for (int j = 0; j < 8; ++j) t[j] = sp[64 * j];
;                 _Pragma("unroll 1") for (int s = 1; s < nslab; ++s) { sp += (size_t)NS * D / 4;
; #pragma unroll
;                     for (int j = 0; j < 8; ++j) t[j] += sp[64 * j]; }
;                 if (TSRC == 2) { const GAS v2u* pp = (const GAS v2u*)(PUP + (size_t)r * D) + lane;
; #pragma unroll
;                     for (int j = 0; j < 8; ++j) { const v2u pw = pp[64 * j]; const f32x4 p = (f32x4){bflo(pw.x), bfhi(pw.x), bflo(pw.y), bfhi(pw.y)}; t[j] = (f32x4){sigmf(t[j][0]), sigmf(t[j][1]), sigmf(t[j][2]), sigmf(t[j][3])} * p; } }
; #pragma unroll
;                 for (int j = 0; j < 8; ++j) ss += dot4(t[j], t[j]);
;             } else {
; #pragma unroll
;                 for (int j = 0; j < 8; ++j) { const v2u tw = tp[64 * j]; t[j] = (f32x4){bflo(tw.x), bfhi(tw.x), bflo(tw.y), bfhi(tw.y)}; ss += dot4(t[j], t[j]); }
.Lrowpf1899_conv:
	v_and_b32_e32 v61, 0xffff0000, v34
	v_and_b32_e32 v59, 0xffff0000, v35
	v_lshlrev_b32_e32 v60, 16, v34
	v_lshlrev_b32_e32 v58, 16, v35
	v_and_b32_e32 v107, 0xffff0000, v37
	v_and_b32_e32 v106, 0xffff0000, v36
	v_and_b32_e32 v53, 0xffff0000, v38
	v_and_b32_e32 v49, 0xffff0000, v39
	v_lshlrev_b32_e32 v109, 16, v40
	v_and_b32_e32 v57, 0xffff0000, v40
	v_lshlrev_b32_e32 v45, 16, v43
	v_lshlrev_b32_e32 v44, 16, v42
	v_and_b32_e32 v111, 0xffff0000, v43
	v_and_b32_e32 v110, 0xffff0000, v42
	v_lshlrev_b32_e32 v43, 16, v90
	v_mul_f32_e32 v42, v59, v59
	v_mul_f32_e32 v56, v61, v61
	v_lshlrev_b32_e32 v55, 16, v37
	v_lshlrev_b32_e32 v54, 16, v36
	v_lshlrev_b32_e32 v52, 16, v38
	v_lshlrev_b32_e32 v48, 16, v39
	v_lshlrev_b32_e32 v38, 16, v62
	v_and_b32_e32 v39, 0xffff0000, v62
	v_lshlrev_b32_e32 v36, 16, v63
	v_and_b32_e32 v37, 0xffff0000, v63
	v_and_b32_e32 v35, 0xffff0000, v90
	v_lshlrev_b32_e32 v32, 16, v91
	v_and_b32_e32 v33, 0xffff0000, v91
	v_pk_mul_f32 v[62:63], v[106:107], v[106:107]
	v_mov_b32_e32 v91, v109
	v_mul_f32_e32 v90, v53, v53
	v_mul_f32_e32 v108, v49, v49
	v_pk_fma_f32 v[120:121], v[58:59], v[58:59], v[42:43] op_sel_hi:[1,1,0]
	v_pk_fma_f32 v[122:123], v[60:61], v[60:61], v[56:57] op_sel_hi:[1,1,0]
	v_lshlrev_b32_e32 v50, 16, v41
	v_and_b32_e32 v51, 0xffff0000, v41
	v_pk_fma_f32 v[62:63], v[54:55], v[54:55], v[62:63]
	v_pk_fma_f32 v[124:125], v[52:53], v[52:53], v[90:91] op_sel_hi:[1,1,0]
	v_pk_fma_f32 v[126:127], v[48:49], v[48:49], v[108:109] op_sel_hi:[1,1,0]
	v_mov_b32_e32 v108, v122
	v_mov_b32_e32 v90, v120
	v_mul_f32_e32 v105, v57, v57
	v_mul_f32_e32 v130, v50, v50
	v_mul_f32_e32 v131, v51, v51
	v_pk_add_f32 v[120:121], v[122:123], v[120:121]
	v_pk_add_f32 v[62:63], v[62:63], v[62:63] op_sel:[0,1] op_sel_hi:[1,0]
	v_pk_mul_f32 v[90:91], v[108:109], v[90:91]
	v_mov_b32_e32 v125, v130
	v_mov_b32_e32 v127, v131
	v_mov_b32_e32 v63, v105
	v_mov_b32_e32 v121, v91
	v_pk_mul_f32 v[112:113], v[110:111], v[110:111]
	v_pk_add_f32 v[122:123], v[124:125], v[126:127]
	v_pk_add_f32 v[62:63], v[120:121], v[62:63]
	v_lshlrev_b32_e32 v41, 16, v47
	v_lshlrev_b32_e32 v40, 16, v46
	v_and_b32_e32 v47, 0xffff0000, v47
	v_and_b32_e32 v46, 0xffff0000, v46
	v_pk_fma_f32 v[112:113], v[44:45], v[44:45], v[112:113]
	v_pk_add_f32 v[62:63], v[62:63], v[122:123]
	v_pk_mul_f32 v[114:115], v[46:47], v[46:47]
	v_mov_b32_e32 v117, v43
	v_mul_f32_e32 v116, v39, v39
	v_pk_add_f32 v[112:113], v[112:113], v[112:113] op_sel:[0,1] op_sel_hi:[1,0]
	v_pk_add_f32 v[62:63], v[62:63], v[62:63] op_sel:[0,1] op_sel_hi:[1,0]
	v_mul_f32_e32 v118, v37, v37
	v_pk_fma_f32 v[114:115], v[40:41], v[40:41], v[114:115]
	v_pk_fma_f32 v[128:129], v[38:39], v[38:39], v[116:117] op_sel_hi:[1,1,0]
	v_mov_b32_e32 v116, v112
	v_mov_b32_e32 v42, v62
	v_mul_f32_e32 v132, v35, v35
	v_mul_f32_e32 v133, v32, v32
	v_mul_f32_e32 v134, v33, v33
	v_mov_b32_e32 v34, v43
	v_pk_fma_f32 v[118:119], v[36:37], v[36:37], v[118:119] op_sel_hi:[1,1,0]
	v_pk_add_f32 v[114:115], v[114:115], v[114:115] op_sel:[0,1] op_sel_hi:[1,0]
	v_pk_add_f32 v[62:63], v[62:63], v[112:113]
	v_pk_mul_f32 v[42:43], v[42:43], v[116:117]
	v_mov_b32_e32 v129, v133
	v_mov_b32_e32 v119, v134
	v_mov_b32_e32 v115, v132
	v_mov_b32_e32 v63, v43
	v_pk_add_f32 v[118:119], v[128:129], v[118:119]
	v_pk_add_f32 v[42:43], v[62:63], v[114:115]
	v_mov_b32_e32 v56, v109
	v_pk_add_f32 v[42:43], v[42:43], v[118:119]
	v_mov_b32_e32 v63, v107
	v_add_f32_e32 v90, v42, v43
	v_mov_b32_e32 v43, v47
	v_mov_b32_e32 v42, v41
	v_mov_b32_e32 v41, v46
	v_mov_b32_e32 v47, v111
	v_mov_b32_e32 v46, v45
	v_mov_b32_e32 v45, v110
	v_mov_b32_e32 v62, v55
	v_mov_b32_e32 v55, v106
